# peer top-k combine stage hand-written: tournament arg-max with packed frontier positions instead of the serial scan
# speedup vs baseline: 1.0100x; 1.0100x over previous
; DI void peer_topk_item(const Params& p, int tt128, int head, char* smem) {
;     ...
;   if (tid < 128) {
;     const float* av = topv + tid * 16;
;     const float* bv = topv + (128 + tid) * 16;
;     const unsigned char* ai = topi + tid * 16;
;     const unsigned char* bi_ = topi + (128 + tid) * 16;
;     float cur[16]; int pp[16];
;     const float b0 = bv[0];
; #pragma unroll
;     for (int i = 0; i < 16; ++i) { cur[i] = av[i] + b0; pp[i] = 0; }
;     float sel[16]; int eid[16];
; #pragma unroll
;     for (int r = 0; r < 16; ++r) {
;       float best = cur[0]; int bi = 0; int bj = pp[0];
; #pragma unroll
;       for (int i = 1; i < 16; ++i) if (cur[i] > best) { best = cur[i]; bi = i; bj = pp[i]; }
;       sel[r] = best;
;       eid[r] = (int)ai[bi] * 128 + (int)bi_[bj];
;       const int nj = bj + 1;
;       const float nv = (nj < 16) ? (av[bi] + bv[nj & 15]) : -INFINITY;
; #pragma unroll
;       for (int i = 0; i < 16; ++i) { cur[i] = (i == bi) ? nv : cur[i]; pp[i] = (i == bi) ? nj : pp[i]; }
;     }
.LBB0_968:
	s_or_b64 exec, exec, s[52:53]
	s_barrier
	s_and_saveexec_b64 s[0:1], s[6:7]
	s_cbranch_execz .LBB0_962
	ds_read_b128 v[0:3], v55
	ds_read_b128 v[4:7], v55 offset:16
	ds_read_b128 v[8:11], v55 offset:32
	ds_read_b128 v[12:15], v55 offset:48
	ds_read_b32 v27, v56
	v_mov_b32_e32 v24, 0
	v_mov_b32_e32 v25, 0
	v_mov_b32_e32 v26, 0xff800000
	s_waitcnt lgkmcnt(0)
	v_add_f32_e32 v0, v27, v0
	v_add_f32_e32 v1, v27, v1
	v_add_f32_e32 v2, v27, v2
	v_add_f32_e32 v3, v27, v3
	v_add_f32_e32 v4, v27, v4
	v_add_f32_e32 v5, v27, v5
	v_add_f32_e32 v6, v27, v6
	v_add_f32_e32 v7, v27, v7
	v_add_f32_e32 v8, v27, v8
	v_add_f32_e32 v9, v27, v9
	v_add_f32_e32 v10, v27, v10
	v_add_f32_e32 v11, v27, v11
	v_add_f32_e32 v12, v27, v12
	v_add_f32_e32 v13, v27, v13
	v_add_f32_e32 v14, v27, v14
	v_add_f32_e32 v15, v27, v15
	v_cmp_gt_f32_e64 s[8:9], v1, v0
	v_cmp_gt_f32_e64 s[10:11], v3, v2
	v_cmp_gt_f32_e64 s[12:13], v5, v4
	v_cmp_gt_f32_e64 s[24:25], v7, v6
	v_cmp_gt_f32_e64 s[26:27], v9, v8
	v_cmp_gt_f32_e64 s[28:29], v11, v10
	v_cmp_gt_f32_e64 s[30:31], v13, v12
	v_cmp_gt_f32_e64 s[34:35], v15, v14
	v_cndmask_b32_e64 v16, v0, v1, s[8:9]
	v_cndmask_b32_e64 v141, 0, 1, s[8:9]
	v_cndmask_b32_e64 v17, v2, v3, s[10:11]
	v_cndmask_b32_e64 v142, 2, 3, s[10:11]
	v_cndmask_b32_e64 v18, v4, v5, s[12:13]
	v_cndmask_b32_e64 v143, 4, 5, s[12:13]
	v_cndmask_b32_e64 v19, v6, v7, s[24:25]
	v_cndmask_b32_e64 v144, 6, 7, s[24:25]
	v_cndmask_b32_e64 v20, v8, v9, s[26:27]
	v_cndmask_b32_e64 v145, 8, 9, s[26:27]
	v_cndmask_b32_e64 v21, v10, v11, s[28:29]
	v_cndmask_b32_e64 v146, 10, 11, s[28:29]
	v_cndmask_b32_e64 v22, v12, v13, s[30:31]
	v_cndmask_b32_e64 v147, 12, 13, s[30:31]
	v_cndmask_b32_e64 v23, v14, v15, s[34:35]
	v_cndmask_b32_e64 v148, 14, 15, s[34:35]
	v_cmp_gt_f32_e64 s[8:9], v17, v16
	v_cmp_gt_f32_e64 s[10:11], v19, v18
	v_cmp_gt_f32_e64 s[12:13], v21, v20
	v_cmp_gt_f32_e64 s[24:25], v23, v22
	v_cndmask_b32_e64 v16, v16, v17, s[8:9]
	v_cndmask_b32_e64 v141, v141, v142, s[8:9]
	v_cndmask_b32_e64 v18, v18, v19, s[10:11]
	v_cndmask_b32_e64 v143, v143, v144, s[10:11]
	v_cndmask_b32_e64 v20, v20, v21, s[12:13]
	v_cndmask_b32_e64 v145, v145, v146, s[12:13]
	v_cndmask_b32_e64 v22, v22, v23, s[24:25]
	v_cndmask_b32_e64 v147, v147, v148, s[24:25]
	v_cmp_gt_f32_e64 s[8:9], v18, v16
	v_cmp_gt_f32_e64 s[10:11], v22, v20
	s_nop 0
	v_cndmask_b32_e64 v16, v16, v18, s[8:9]
	v_cndmask_b32_e64 v141, v141, v143, s[8:9]
	v_cndmask_b32_e64 v20, v20, v22, s[10:11]
	v_cndmask_b32_e64 v145, v145, v147, s[10:11]
	v_cmp_gt_f32_e64 s[8:9], v20, v16
	s_nop 1
	v_cndmask_b32_e64 v16, v16, v20, s[8:9]
	v_cndmask_b32_e64 v141, v141, v145, s[8:9]
	v_mov_b32_e32 v124, v16
	v_add_u32_e32 v28, v57, v141
	ds_read_u8 v19, v28
	v_cmp_gt_u32_e64 s[62:63], 8, v141
	v_and_b32_e32 v29, 7, v141
	v_lshlrev_b32_e32 v29, 2, v29
	v_cndmask_b32_e64 v30, v25, v24, s[62:63]
	v_bfe_u32 v31, v30, v29, 4
	v_add_u32_e32 v52, v58, v31
	ds_read_u8 v21, v52
	v_lshl_add_u32 v27, v141, 2, v55
	ds_read_b32 v17, v27
	v_add_u32_e32 v53, 1, v31
	v_and_b32_e32 v27, 15, v53
	v_lshl_add_u32 v27, v27, 2, v56
	ds_read_b32 v18, v27
	v_cmp_gt_u32_e64 s[60:61], 15, v31
	v_lshlrev_b32_e64 v28, v29, 1
	s_nop 0
	v_cndmask_b32_e64 v28, 0, v28, s[60:61]
	v_cndmask_b32_e64 v30, 0, v28, s[62:63]
	v_sub_u32_e32 v28, v28, v30
	v_add_u32_e32 v24, v24, v30
	v_add_u32_e32 v25, v25, v28
	v_cmp_eq_u32_e64 s[8:9], 0, v141
	v_cmp_eq_u32_e64 s[10:11], 1, v141
	v_cmp_eq_u32_e64 s[12:13], 2, v141
	v_cmp_eq_u32_e64 s[24:25], 3, v141
	v_cmp_eq_u32_e64 s[26:27], 4, v141
	v_cmp_eq_u32_e64 s[28:29], 5, v141
	v_cmp_eq_u32_e64 s[30:31], 6, v141
	v_cmp_eq_u32_e64 s[34:35], 7, v141
	v_cmp_eq_u32_e64 s[36:37], 8, v141
	v_cmp_eq_u32_e64 s[38:39], 9, v141
	v_cmp_eq_u32_e64 s[40:41], 10, v141
	v_cmp_eq_u32_e64 s[42:43], 11, v141
	v_cmp_eq_u32_e64 s[44:45], 12, v141
	v_cmp_eq_u32_e64 s[46:47], 13, v141
	v_cmp_eq_u32_e64 s[60:61], 14, v141
	v_cmp_eq_u32_e64 s[62:63], 15, v141
	s_waitcnt lgkmcnt(0)
	v_cmp_gt_u32_e64 s[4:5], 16, v53
	v_add_f32_e32 v17, v17, v18
	v_lshl_add_u32 v32, v19, 7, v21
	v_cndmask_b32_e64 v17, v26, v17, s[4:5]
	v_cndmask_b32_e64 v0, v0, v17, s[8:9]
	v_cndmask_b32_e64 v1, v1, v17, s[10:11]
	v_cndmask_b32_e64 v2, v2, v17, s[12:13]
	v_cndmask_b32_e64 v3, v3, v17, s[24:25]
	v_cndmask_b32_e64 v4, v4, v17, s[26:27]
	v_cndmask_b32_e64 v5, v5, v17, s[28:29]
	v_cndmask_b32_e64 v6, v6, v17, s[30:31]
	v_cndmask_b32_e64 v7, v7, v17, s[34:35]
	v_cndmask_b32_e64 v8, v8, v17, s[36:37]
	v_cndmask_b32_e64 v9, v9, v17, s[38:39]
	v_cndmask_b32_e64 v10, v10, v17, s[40:41]
	v_cndmask_b32_e64 v11, v11, v17, s[42:43]
	v_cndmask_b32_e64 v12, v12, v17, s[44:45]
	v_cndmask_b32_e64 v13, v13, v17, s[46:47]
	v_cndmask_b32_e64 v14, v14, v17, s[60:61]
	v_cndmask_b32_e64 v15, v15, v17, s[62:63]
	v_cmp_gt_f32_e64 s[8:9], v1, v0
	v_cmp_gt_f32_e64 s[10:11], v3, v2
	v_cmp_gt_f32_e64 s[12:13], v5, v4
	v_cmp_gt_f32_e64 s[24:25], v7, v6
	v_cmp_gt_f32_e64 s[26:27], v9, v8
	v_cmp_gt_f32_e64 s[28:29], v11, v10
	v_cmp_gt_f32_e64 s[30:31], v13, v12
	v_cmp_gt_f32_e64 s[34:35], v15, v14
	v_cndmask_b32_e64 v16, v0, v1, s[8:9]
	v_cndmask_b32_e64 v141, 0, 1, s[8:9]
	v_cndmask_b32_e64 v17, v2, v3, s[10:11]
	v_cndmask_b32_e64 v142, 2, 3, s[10:11]
	v_cndmask_b32_e64 v18, v4, v5, s[12:13]
	v_cndmask_b32_e64 v143, 4, 5, s[12:13]
	v_cndmask_b32_e64 v19, v6, v7, s[24:25]
	v_cndmask_b32_e64 v144, 6, 7, s[24:25]
	v_cndmask_b32_e64 v20, v8, v9, s[26:27]
	v_cndmask_b32_e64 v145, 8, 9, s[26:27]
	v_cndmask_b32_e64 v21, v10, v11, s[28:29]
	v_cndmask_b32_e64 v146, 10, 11, s[28:29]
	v_cndmask_b32_e64 v22, v12, v13, s[30:31]
	v_cndmask_b32_e64 v147, 12, 13, s[30:31]
	v_cndmask_b32_e64 v23, v14, v15, s[34:35]
; DI void peer_topk_item(const Params& p, int tt128, int head, char* smem) {
;     ...
;     for (int r = 0; r < 16; ++r) {
;       float best = cur[0]; int bi = 0; int bj = pp[0];
; #pragma unroll
;       for (int i = 1; i < 16; ++i) if (cur[i] > best) { best = cur[i]; bi = i; bj = pp[i]; }
;       sel[r] = best;
;       eid[r] = (int)ai[bi] * 128 + (int)bi_[bj];
;       const int nj = bj + 1;
;       const float nv = (nj < 16) ? (av[bi] + bv[nj & 15]) : -INFINITY;
; #pragma unroll
;       for (int i = 0; i < 16; ++i) { cur[i] = (i == bi) ? nv : cur[i]; pp[i] = (i == bi) ? nj : pp[i]; }
;     }
	v_cndmask_b32_e64 v148, 14, 15, s[34:35]
	v_cmp_gt_f32_e64 s[8:9], v17, v16
	v_cmp_gt_f32_e64 s[10:11], v19, v18
	v_cmp_gt_f32_e64 s[12:13], v21, v20
	v_cmp_gt_f32_e64 s[24:25], v23, v22
	v_cndmask_b32_e64 v16, v16, v17, s[8:9]
	v_cndmask_b32_e64 v141, v141, v142, s[8:9]
	v_cndmask_b32_e64 v18, v18, v19, s[10:11]
	v_cndmask_b32_e64 v143, v143, v144, s[10:11]
	v_cndmask_b32_e64 v20, v20, v21, s[12:13]
	v_cndmask_b32_e64 v145, v145, v146, s[12:13]
	v_cndmask_b32_e64 v22, v22, v23, s[24:25]
	v_cndmask_b32_e64 v147, v147, v148, s[24:25]
	v_cmp_gt_f32_e64 s[8:9], v18, v16
	v_cmp_gt_f32_e64 s[10:11], v22, v20
	s_nop 0
	v_cndmask_b32_e64 v16, v16, v18, s[8:9]
	v_cndmask_b32_e64 v141, v141, v143, s[8:9]
	v_cndmask_b32_e64 v20, v20, v22, s[10:11]
	v_cndmask_b32_e64 v145, v145, v147, s[10:11]
	v_cmp_gt_f32_e64 s[8:9], v20, v16
	s_nop 1
	v_cndmask_b32_e64 v16, v16, v20, s[8:9]
	v_cndmask_b32_e64 v141, v141, v145, s[8:9]
	v_mov_b32_e32 v125, v16
	v_add_u32_e32 v28, v57, v141
	ds_read_u8 v19, v28
	v_cmp_gt_u32_e64 s[62:63], 8, v141
	v_and_b32_e32 v29, 7, v141
	v_lshlrev_b32_e32 v29, 2, v29
	v_cndmask_b32_e64 v30, v25, v24, s[62:63]
	v_bfe_u32 v31, v30, v29, 4
	v_add_u32_e32 v52, v58, v31
	ds_read_u8 v21, v52
	v_lshl_add_u32 v27, v141, 2, v55
	ds_read_b32 v17, v27
	v_add_u32_e32 v53, 1, v31
	v_and_b32_e32 v27, 15, v53
	v_lshl_add_u32 v27, v27, 2, v56
	ds_read_b32 v18, v27
	v_cmp_gt_u32_e64 s[60:61], 15, v31
	v_lshlrev_b32_e64 v28, v29, 1
	s_nop 0
	v_cndmask_b32_e64 v28, 0, v28, s[60:61]
	v_cndmask_b32_e64 v30, 0, v28, s[62:63]
	v_sub_u32_e32 v28, v28, v30
	v_add_u32_e32 v24, v24, v30
	v_add_u32_e32 v25, v25, v28
	v_cmp_eq_u32_e64 s[8:9], 0, v141
	v_cmp_eq_u32_e64 s[10:11], 1, v141
	v_cmp_eq_u32_e64 s[12:13], 2, v141
	v_cmp_eq_u32_e64 s[24:25], 3, v141
	v_cmp_eq_u32_e64 s[26:27], 4, v141
	v_cmp_eq_u32_e64 s[28:29], 5, v141
	v_cmp_eq_u32_e64 s[30:31], 6, v141
	v_cmp_eq_u32_e64 s[34:35], 7, v141
	v_cmp_eq_u32_e64 s[36:37], 8, v141
	v_cmp_eq_u32_e64 s[38:39], 9, v141
	v_cmp_eq_u32_e64 s[40:41], 10, v141
	v_cmp_eq_u32_e64 s[42:43], 11, v141
	v_cmp_eq_u32_e64 s[44:45], 12, v141
	v_cmp_eq_u32_e64 s[46:47], 13, v141
	v_cmp_eq_u32_e64 s[60:61], 14, v141
	v_cmp_eq_u32_e64 s[62:63], 15, v141
	s_waitcnt lgkmcnt(0)
	v_cmp_gt_u32_e64 s[4:5], 16, v53
	v_add_f32_e32 v17, v17, v18
	v_lshl_add_u32 v33, v19, 7, v21
	v_cndmask_b32_e64 v17, v26, v17, s[4:5]
	v_cndmask_b32_e64 v0, v0, v17, s[8:9]
	v_cndmask_b32_e64 v1, v1, v17, s[10:11]
	v_cndmask_b32_e64 v2, v2, v17, s[12:13]
	v_cndmask_b32_e64 v3, v3, v17, s[24:25]
	v_cndmask_b32_e64 v4, v4, v17, s[26:27]
	v_cndmask_b32_e64 v5, v5, v17, s[28:29]
	v_cndmask_b32_e64 v6, v6, v17, s[30:31]
	v_cndmask_b32_e64 v7, v7, v17, s[34:35]
	v_cndmask_b32_e64 v8, v8, v17, s[36:37]
	v_cndmask_b32_e64 v9, v9, v17, s[38:39]
	v_cndmask_b32_e64 v10, v10, v17, s[40:41]
	v_cndmask_b32_e64 v11, v11, v17, s[42:43]
	v_cndmask_b32_e64 v12, v12, v17, s[44:45]
	v_cndmask_b32_e64 v13, v13, v17, s[46:47]
	v_cndmask_b32_e64 v14, v14, v17, s[60:61]
	v_cndmask_b32_e64 v15, v15, v17, s[62:63]
	v_cmp_gt_f32_e64 s[8:9], v1, v0
	v_cmp_gt_f32_e64 s[10:11], v3, v2
	v_cmp_gt_f32_e64 s[12:13], v5, v4
	v_cmp_gt_f32_e64 s[24:25], v7, v6
	v_cmp_gt_f32_e64 s[26:27], v9, v8
	v_cmp_gt_f32_e64 s[28:29], v11, v10
	v_cmp_gt_f32_e64 s[30:31], v13, v12
	v_cmp_gt_f32_e64 s[34:35], v15, v14
	v_cndmask_b32_e64 v16, v0, v1, s[8:9]
	v_cndmask_b32_e64 v141, 0, 1, s[8:9]
	v_cndmask_b32_e64 v17, v2, v3, s[10:11]
	v_cndmask_b32_e64 v142, 2, 3, s[10:11]
	v_cndmask_b32_e64 v18, v4, v5, s[12:13]
	v_cndmask_b32_e64 v143, 4, 5, s[12:13]
	v_cndmask_b32_e64 v19, v6, v7, s[24:25]
	v_cndmask_b32_e64 v144, 6, 7, s[24:25]
	v_cndmask_b32_e64 v20, v8, v9, s[26:27]
	v_cndmask_b32_e64 v145, 8, 9, s[26:27]
	v_cndmask_b32_e64 v21, v10, v11, s[28:29]
	v_cndmask_b32_e64 v146, 10, 11, s[28:29]
	v_cndmask_b32_e64 v22, v12, v13, s[30:31]
	v_cndmask_b32_e64 v147, 12, 13, s[30:31]
	v_cndmask_b32_e64 v23, v14, v15, s[34:35]
	v_cndmask_b32_e64 v148, 14, 15, s[34:35]
	v_cmp_gt_f32_e64 s[8:9], v17, v16
	v_cmp_gt_f32_e64 s[10:11], v19, v18
	v_cmp_gt_f32_e64 s[12:13], v21, v20
	v_cmp_gt_f32_e64 s[24:25], v23, v22
	v_cndmask_b32_e64 v16, v16, v17, s[8:9]
	v_cndmask_b32_e64 v141, v141, v142, s[8:9]
	v_cndmask_b32_e64 v18, v18, v19, s[10:11]
	v_cndmask_b32_e64 v143, v143, v144, s[10:11]
	v_cndmask_b32_e64 v20, v20, v21, s[12:13]
	v_cndmask_b32_e64 v145, v145, v146, s[12:13]
	v_cndmask_b32_e64 v22, v22, v23, s[24:25]
	v_cndmask_b32_e64 v147, v147, v148, s[24:25]
	v_cmp_gt_f32_e64 s[8:9], v18, v16
	v_cmp_gt_f32_e64 s[10:11], v22, v20
	s_nop 0
	v_cndmask_b32_e64 v16, v16, v18, s[8:9]
	v_cndmask_b32_e64 v141, v141, v143, s[8:9]
	v_cndmask_b32_e64 v20, v20, v22, s[10:11]
	v_cndmask_b32_e64 v145, v145, v147, s[10:11]
	v_cmp_gt_f32_e64 s[8:9], v20, v16
	s_nop 1
	v_cndmask_b32_e64 v16, v16, v20, s[8:9]
	v_cndmask_b32_e64 v141, v141, v145, s[8:9]
	v_mov_b32_e32 v126, v16
	v_add_u32_e32 v28, v57, v141
	ds_read_u8 v19, v28
	v_cmp_gt_u32_e64 s[62:63], 8, v141
	v_and_b32_e32 v29, 7, v141
	v_lshlrev_b32_e32 v29, 2, v29
	v_cndmask_b32_e64 v30, v25, v24, s[62:63]
	v_bfe_u32 v31, v30, v29, 4
	v_add_u32_e32 v52, v58, v31
	ds_read_u8 v21, v52
	v_lshl_add_u32 v27, v141, 2, v55
	ds_read_b32 v17, v27
	v_add_u32_e32 v53, 1, v31
	v_and_b32_e32 v27, 15, v53
	v_lshl_add_u32 v27, v27, 2, v56
	ds_read_b32 v18, v27
	v_cmp_gt_u32_e64 s[60:61], 15, v31
	v_lshlrev_b32_e64 v28, v29, 1
	s_nop 0
	v_cndmask_b32_e64 v28, 0, v28, s[60:61]
	v_cndmask_b32_e64 v30, 0, v28, s[62:63]
	v_sub_u32_e32 v28, v28, v30
	v_add_u32_e32 v24, v24, v30
	v_add_u32_e32 v25, v25, v28
	v_cmp_eq_u32_e64 s[8:9], 0, v141
	v_cmp_eq_u32_e64 s[10:11], 1, v141
	v_cmp_eq_u32_e64 s[12:13], 2, v141
	v_cmp_eq_u32_e64 s[24:25], 3, v141
	v_cmp_eq_u32_e64 s[26:27], 4, v141
	v_cmp_eq_u32_e64 s[28:29], 5, v141
	v_cmp_eq_u32_e64 s[30:31], 6, v141
	v_cmp_eq_u32_e64 s[34:35], 7, v141
	v_cmp_eq_u32_e64 s[36:37], 8, v141
	v_cmp_eq_u32_e64 s[38:39], 9, v141
	v_cmp_eq_u32_e64 s[40:41], 10, v141
	v_cmp_eq_u32_e64 s[42:43], 11, v141
	v_cmp_eq_u32_e64 s[44:45], 12, v141
	v_cmp_eq_u32_e64 s[46:47], 13, v141
	v_cmp_eq_u32_e64 s[60:61], 14, v141
	v_cmp_eq_u32_e64 s[62:63], 15, v141
	s_waitcnt lgkmcnt(0)
; DI void peer_topk_item(const Params& p, int tt128, int head, char* smem) {
;     ...
; #pragma unroll
;     for (int r = 0; r < 16; ++r) {
;       float best = cur[0]; int bi = 0; int bj = pp[0];
; #pragma unroll
;       for (int i = 1; i < 16; ++i) if (cur[i] > best) { best = cur[i]; bi = i; bj = pp[i]; }
;       sel[r] = best;
;       eid[r] = (int)ai[bi] * 128 + (int)bi_[bj];
;       const int nj = bj + 1;
;       const float nv = (nj < 16) ? (av[bi] + bv[nj & 15]) : -INFINITY;
; #pragma unroll
;       for (int i = 0; i < 16; ++i) { cur[i] = (i == bi) ? nv : cur[i]; pp[i] = (i == bi) ? nj : pp[i]; }
;     }
	v_cmp_gt_u32_e64 s[4:5], 16, v53
	v_add_f32_e32 v17, v17, v18
	v_lshl_add_u32 v34, v19, 7, v21
	v_cndmask_b32_e64 v17, v26, v17, s[4:5]
	v_cndmask_b32_e64 v0, v0, v17, s[8:9]
	v_cndmask_b32_e64 v1, v1, v17, s[10:11]
	v_cndmask_b32_e64 v2, v2, v17, s[12:13]
	v_cndmask_b32_e64 v3, v3, v17, s[24:25]
	v_cndmask_b32_e64 v4, v4, v17, s[26:27]
	v_cndmask_b32_e64 v5, v5, v17, s[28:29]
	v_cndmask_b32_e64 v6, v6, v17, s[30:31]
	v_cndmask_b32_e64 v7, v7, v17, s[34:35]
	v_cndmask_b32_e64 v8, v8, v17, s[36:37]
	v_cndmask_b32_e64 v9, v9, v17, s[38:39]
	v_cndmask_b32_e64 v10, v10, v17, s[40:41]
	v_cndmask_b32_e64 v11, v11, v17, s[42:43]
	v_cndmask_b32_e64 v12, v12, v17, s[44:45]
	v_cndmask_b32_e64 v13, v13, v17, s[46:47]
	v_cndmask_b32_e64 v14, v14, v17, s[60:61]
	v_cndmask_b32_e64 v15, v15, v17, s[62:63]
	v_cmp_gt_f32_e64 s[8:9], v1, v0
	v_cmp_gt_f32_e64 s[10:11], v3, v2
	v_cmp_gt_f32_e64 s[12:13], v5, v4
	v_cmp_gt_f32_e64 s[24:25], v7, v6
	v_cmp_gt_f32_e64 s[26:27], v9, v8
	v_cmp_gt_f32_e64 s[28:29], v11, v10
	v_cmp_gt_f32_e64 s[30:31], v13, v12
	v_cmp_gt_f32_e64 s[34:35], v15, v14
	v_cndmask_b32_e64 v16, v0, v1, s[8:9]
	v_cndmask_b32_e64 v141, 0, 1, s[8:9]
	v_cndmask_b32_e64 v17, v2, v3, s[10:11]
	v_cndmask_b32_e64 v142, 2, 3, s[10:11]
	v_cndmask_b32_e64 v18, v4, v5, s[12:13]
	v_cndmask_b32_e64 v143, 4, 5, s[12:13]
	v_cndmask_b32_e64 v19, v6, v7, s[24:25]
	v_cndmask_b32_e64 v144, 6, 7, s[24:25]
	v_cndmask_b32_e64 v20, v8, v9, s[26:27]
	v_cndmask_b32_e64 v145, 8, 9, s[26:27]
	v_cndmask_b32_e64 v21, v10, v11, s[28:29]
	v_cndmask_b32_e64 v146, 10, 11, s[28:29]
	v_cndmask_b32_e64 v22, v12, v13, s[30:31]
	v_cndmask_b32_e64 v147, 12, 13, s[30:31]
	v_cndmask_b32_e64 v23, v14, v15, s[34:35]
	v_cndmask_b32_e64 v148, 14, 15, s[34:35]
	v_cmp_gt_f32_e64 s[8:9], v17, v16
	v_cmp_gt_f32_e64 s[10:11], v19, v18
	v_cmp_gt_f32_e64 s[12:13], v21, v20
	v_cmp_gt_f32_e64 s[24:25], v23, v22
	v_cndmask_b32_e64 v16, v16, v17, s[8:9]
	v_cndmask_b32_e64 v141, v141, v142, s[8:9]
	v_cndmask_b32_e64 v18, v18, v19, s[10:11]
	v_cndmask_b32_e64 v143, v143, v144, s[10:11]
	v_cndmask_b32_e64 v20, v20, v21, s[12:13]
	v_cndmask_b32_e64 v145, v145, v146, s[12:13]
	v_cndmask_b32_e64 v22, v22, v23, s[24:25]
	v_cndmask_b32_e64 v147, v147, v148, s[24:25]
	v_cmp_gt_f32_e64 s[8:9], v18, v16
	v_cmp_gt_f32_e64 s[10:11], v22, v20
	s_nop 0
	v_cndmask_b32_e64 v16, v16, v18, s[8:9]
	v_cndmask_b32_e64 v141, v141, v143, s[8:9]
	v_cndmask_b32_e64 v20, v20, v22, s[10:11]
	v_cndmask_b32_e64 v145, v145, v147, s[10:11]
	v_cmp_gt_f32_e64 s[8:9], v20, v16
	s_nop 1
	v_cndmask_b32_e64 v16, v16, v20, s[8:9]
	v_cndmask_b32_e64 v141, v141, v145, s[8:9]
	v_mov_b32_e32 v127, v16
	v_add_u32_e32 v28, v57, v141
	ds_read_u8 v19, v28
	v_cmp_gt_u32_e64 s[62:63], 8, v141
	v_and_b32_e32 v29, 7, v141
	v_lshlrev_b32_e32 v29, 2, v29
	v_cndmask_b32_e64 v30, v25, v24, s[62:63]
	v_bfe_u32 v31, v30, v29, 4
	v_add_u32_e32 v52, v58, v31
	ds_read_u8 v21, v52
	v_lshl_add_u32 v27, v141, 2, v55
	ds_read_b32 v17, v27
	v_add_u32_e32 v53, 1, v31
	v_and_b32_e32 v27, 15, v53
	v_lshl_add_u32 v27, v27, 2, v56
	ds_read_b32 v18, v27
	v_cmp_gt_u32_e64 s[60:61], 15, v31
	v_lshlrev_b32_e64 v28, v29, 1
	s_nop 0
	v_cndmask_b32_e64 v28, 0, v28, s[60:61]
	v_cndmask_b32_e64 v30, 0, v28, s[62:63]
	v_sub_u32_e32 v28, v28, v30
	v_add_u32_e32 v24, v24, v30
	v_add_u32_e32 v25, v25, v28
	v_cmp_eq_u32_e64 s[8:9], 0, v141
	v_cmp_eq_u32_e64 s[10:11], 1, v141
	v_cmp_eq_u32_e64 s[12:13], 2, v141
	v_cmp_eq_u32_e64 s[24:25], 3, v141
	v_cmp_eq_u32_e64 s[26:27], 4, v141
	v_cmp_eq_u32_e64 s[28:29], 5, v141
	v_cmp_eq_u32_e64 s[30:31], 6, v141
	v_cmp_eq_u32_e64 s[34:35], 7, v141
	v_cmp_eq_u32_e64 s[36:37], 8, v141
	v_cmp_eq_u32_e64 s[38:39], 9, v141
	v_cmp_eq_u32_e64 s[40:41], 10, v141
	v_cmp_eq_u32_e64 s[42:43], 11, v141
	v_cmp_eq_u32_e64 s[44:45], 12, v141
	v_cmp_eq_u32_e64 s[46:47], 13, v141
	v_cmp_eq_u32_e64 s[60:61], 14, v141
	v_cmp_eq_u32_e64 s[62:63], 15, v141
	s_waitcnt lgkmcnt(0)
	v_cmp_gt_u32_e64 s[4:5], 16, v53
	v_add_f32_e32 v17, v17, v18
	v_lshl_add_u32 v35, v19, 7, v21
	v_cndmask_b32_e64 v17, v26, v17, s[4:5]
	v_cndmask_b32_e64 v0, v0, v17, s[8:9]
	v_cndmask_b32_e64 v1, v1, v17, s[10:11]
	v_cndmask_b32_e64 v2, v2, v17, s[12:13]
	v_cndmask_b32_e64 v3, v3, v17, s[24:25]
	v_cndmask_b32_e64 v4, v4, v17, s[26:27]
	v_cndmask_b32_e64 v5, v5, v17, s[28:29]
	v_cndmask_b32_e64 v6, v6, v17, s[30:31]
	v_cndmask_b32_e64 v7, v7, v17, s[34:35]
	v_cndmask_b32_e64 v8, v8, v17, s[36:37]
	v_cndmask_b32_e64 v9, v9, v17, s[38:39]
	v_cndmask_b32_e64 v10, v10, v17, s[40:41]
	v_cndmask_b32_e64 v11, v11, v17, s[42:43]
	v_cndmask_b32_e64 v12, v12, v17, s[44:45]
	v_cndmask_b32_e64 v13, v13, v17, s[46:47]
	v_cndmask_b32_e64 v14, v14, v17, s[60:61]
	v_cndmask_b32_e64 v15, v15, v17, s[62:63]
	v_cmp_gt_f32_e64 s[8:9], v1, v0
	v_cmp_gt_f32_e64 s[10:11], v3, v2
	v_cmp_gt_f32_e64 s[12:13], v5, v4
	v_cmp_gt_f32_e64 s[24:25], v7, v6
	v_cmp_gt_f32_e64 s[26:27], v9, v8
	v_cmp_gt_f32_e64 s[28:29], v11, v10
	v_cmp_gt_f32_e64 s[30:31], v13, v12
	v_cmp_gt_f32_e64 s[34:35], v15, v14
	v_cndmask_b32_e64 v16, v0, v1, s[8:9]
	v_cndmask_b32_e64 v141, 0, 1, s[8:9]
	v_cndmask_b32_e64 v17, v2, v3, s[10:11]
	v_cndmask_b32_e64 v142, 2, 3, s[10:11]
	v_cndmask_b32_e64 v18, v4, v5, s[12:13]
	v_cndmask_b32_e64 v143, 4, 5, s[12:13]
	v_cndmask_b32_e64 v19, v6, v7, s[24:25]
	v_cndmask_b32_e64 v144, 6, 7, s[24:25]
	v_cndmask_b32_e64 v20, v8, v9, s[26:27]
	v_cndmask_b32_e64 v145, 8, 9, s[26:27]
	v_cndmask_b32_e64 v21, v10, v11, s[28:29]
	v_cndmask_b32_e64 v146, 10, 11, s[28:29]
	v_cndmask_b32_e64 v22, v12, v13, s[30:31]
	v_cndmask_b32_e64 v147, 12, 13, s[30:31]
	v_cndmask_b32_e64 v23, v14, v15, s[34:35]
; DI void peer_topk_item(const Params& p, int tt128, int head, char* smem) {
;     ...
; #pragma unroll
;     for (int r = 0; r < 16; ++r) {
;       float best = cur[0]; int bi = 0; int bj = pp[0];
; #pragma unroll
;       for (int i = 1; i < 16; ++i) if (cur[i] > best) { best = cur[i]; bi = i; bj = pp[i]; }
;       sel[r] = best;
;       eid[r] = (int)ai[bi] * 128 + (int)bi_[bj];
;       const int nj = bj + 1;
;       const float nv = (nj < 16) ? (av[bi] + bv[nj & 15]) : -INFINITY;
; #pragma unroll
;       for (int i = 0; i < 16; ++i) { cur[i] = (i == bi) ? nv : cur[i]; pp[i] = (i == bi) ? nj : pp[i]; }
;     }
	v_cndmask_b32_e64 v148, 14, 15, s[34:35]
	v_cmp_gt_f32_e64 s[8:9], v17, v16
	v_cmp_gt_f32_e64 s[10:11], v19, v18
	v_cmp_gt_f32_e64 s[12:13], v21, v20
	v_cmp_gt_f32_e64 s[24:25], v23, v22
	v_cndmask_b32_e64 v16, v16, v17, s[8:9]
	v_cndmask_b32_e64 v141, v141, v142, s[8:9]
	v_cndmask_b32_e64 v18, v18, v19, s[10:11]
	v_cndmask_b32_e64 v143, v143, v144, s[10:11]
	v_cndmask_b32_e64 v20, v20, v21, s[12:13]
	v_cndmask_b32_e64 v145, v145, v146, s[12:13]
	v_cndmask_b32_e64 v22, v22, v23, s[24:25]
	v_cndmask_b32_e64 v147, v147, v148, s[24:25]
	v_cmp_gt_f32_e64 s[8:9], v18, v16
	v_cmp_gt_f32_e64 s[10:11], v22, v20
	s_nop 0
	v_cndmask_b32_e64 v16, v16, v18, s[8:9]
	v_cndmask_b32_e64 v141, v141, v143, s[8:9]
	v_cndmask_b32_e64 v20, v20, v22, s[10:11]
	v_cndmask_b32_e64 v145, v145, v147, s[10:11]
	v_cmp_gt_f32_e64 s[8:9], v20, v16
	s_nop 1
	v_cndmask_b32_e64 v16, v16, v20, s[8:9]
	v_cndmask_b32_e64 v141, v141, v145, s[8:9]
	v_mov_b32_e32 v128, v16
	v_add_u32_e32 v28, v57, v141
	ds_read_u8 v19, v28
	v_cmp_gt_u32_e64 s[62:63], 8, v141
	v_and_b32_e32 v29, 7, v141
	v_lshlrev_b32_e32 v29, 2, v29
	v_cndmask_b32_e64 v30, v25, v24, s[62:63]
	v_bfe_u32 v31, v30, v29, 4
	v_add_u32_e32 v52, v58, v31
	ds_read_u8 v21, v52
	v_lshl_add_u32 v27, v141, 2, v55
	ds_read_b32 v17, v27
	v_add_u32_e32 v53, 1, v31
	v_and_b32_e32 v27, 15, v53
	v_lshl_add_u32 v27, v27, 2, v56
	ds_read_b32 v18, v27
	v_cmp_gt_u32_e64 s[60:61], 15, v31
	v_lshlrev_b32_e64 v28, v29, 1
	s_nop 0
	v_cndmask_b32_e64 v28, 0, v28, s[60:61]
	v_cndmask_b32_e64 v30, 0, v28, s[62:63]
	v_sub_u32_e32 v28, v28, v30
	v_add_u32_e32 v24, v24, v30
	v_add_u32_e32 v25, v25, v28
	v_cmp_eq_u32_e64 s[8:9], 0, v141
	v_cmp_eq_u32_e64 s[10:11], 1, v141
	v_cmp_eq_u32_e64 s[12:13], 2, v141
	v_cmp_eq_u32_e64 s[24:25], 3, v141
	v_cmp_eq_u32_e64 s[26:27], 4, v141
	v_cmp_eq_u32_e64 s[28:29], 5, v141
	v_cmp_eq_u32_e64 s[30:31], 6, v141
	v_cmp_eq_u32_e64 s[34:35], 7, v141
	v_cmp_eq_u32_e64 s[36:37], 8, v141
	v_cmp_eq_u32_e64 s[38:39], 9, v141
	v_cmp_eq_u32_e64 s[40:41], 10, v141
	v_cmp_eq_u32_e64 s[42:43], 11, v141
	v_cmp_eq_u32_e64 s[44:45], 12, v141
	v_cmp_eq_u32_e64 s[46:47], 13, v141
	v_cmp_eq_u32_e64 s[60:61], 14, v141
	v_cmp_eq_u32_e64 s[62:63], 15, v141
	s_waitcnt lgkmcnt(0)
	v_cmp_gt_u32_e64 s[4:5], 16, v53
	v_add_f32_e32 v17, v17, v18
	v_lshl_add_u32 v36, v19, 7, v21
	v_cndmask_b32_e64 v17, v26, v17, s[4:5]
	v_cndmask_b32_e64 v0, v0, v17, s[8:9]
	v_cndmask_b32_e64 v1, v1, v17, s[10:11]
	v_cndmask_b32_e64 v2, v2, v17, s[12:13]
	v_cndmask_b32_e64 v3, v3, v17, s[24:25]
	v_cndmask_b32_e64 v4, v4, v17, s[26:27]
	v_cndmask_b32_e64 v5, v5, v17, s[28:29]
	v_cndmask_b32_e64 v6, v6, v17, s[30:31]
	v_cndmask_b32_e64 v7, v7, v17, s[34:35]
	v_cndmask_b32_e64 v8, v8, v17, s[36:37]
	v_cndmask_b32_e64 v9, v9, v17, s[38:39]
	v_cndmask_b32_e64 v10, v10, v17, s[40:41]
	v_cndmask_b32_e64 v11, v11, v17, s[42:43]
	v_cndmask_b32_e64 v12, v12, v17, s[44:45]
	v_cndmask_b32_e64 v13, v13, v17, s[46:47]
	v_cndmask_b32_e64 v14, v14, v17, s[60:61]
	v_cndmask_b32_e64 v15, v15, v17, s[62:63]
	v_cmp_gt_f32_e64 s[8:9], v1, v0
	v_cmp_gt_f32_e64 s[10:11], v3, v2
	v_cmp_gt_f32_e64 s[12:13], v5, v4
	v_cmp_gt_f32_e64 s[24:25], v7, v6
	v_cmp_gt_f32_e64 s[26:27], v9, v8
	v_cmp_gt_f32_e64 s[28:29], v11, v10
	v_cmp_gt_f32_e64 s[30:31], v13, v12
	v_cmp_gt_f32_e64 s[34:35], v15, v14
	v_cndmask_b32_e64 v16, v0, v1, s[8:9]
	v_cndmask_b32_e64 v141, 0, 1, s[8:9]
	v_cndmask_b32_e64 v17, v2, v3, s[10:11]
	v_cndmask_b32_e64 v142, 2, 3, s[10:11]
	v_cndmask_b32_e64 v18, v4, v5, s[12:13]
	v_cndmask_b32_e64 v143, 4, 5, s[12:13]
	v_cndmask_b32_e64 v19, v6, v7, s[24:25]
	v_cndmask_b32_e64 v144, 6, 7, s[24:25]
	v_cndmask_b32_e64 v20, v8, v9, s[26:27]
	v_cndmask_b32_e64 v145, 8, 9, s[26:27]
	v_cndmask_b32_e64 v21, v10, v11, s[28:29]
	v_cndmask_b32_e64 v146, 10, 11, s[28:29]
	v_cndmask_b32_e64 v22, v12, v13, s[30:31]
	v_cndmask_b32_e64 v147, 12, 13, s[30:31]
	v_cndmask_b32_e64 v23, v14, v15, s[34:35]
	v_cndmask_b32_e64 v148, 14, 15, s[34:35]
	v_cmp_gt_f32_e64 s[8:9], v17, v16
	v_cmp_gt_f32_e64 s[10:11], v19, v18
	v_cmp_gt_f32_e64 s[12:13], v21, v20
	v_cmp_gt_f32_e64 s[24:25], v23, v22
	v_cndmask_b32_e64 v16, v16, v17, s[8:9]
	v_cndmask_b32_e64 v141, v141, v142, s[8:9]
	v_cndmask_b32_e64 v18, v18, v19, s[10:11]
	v_cndmask_b32_e64 v143, v143, v144, s[10:11]
	v_cndmask_b32_e64 v20, v20, v21, s[12:13]
	v_cndmask_b32_e64 v145, v145, v146, s[12:13]
	v_cndmask_b32_e64 v22, v22, v23, s[24:25]
	v_cndmask_b32_e64 v147, v147, v148, s[24:25]
	v_cmp_gt_f32_e64 s[8:9], v18, v16
	v_cmp_gt_f32_e64 s[10:11], v22, v20
	s_nop 0
	v_cndmask_b32_e64 v16, v16, v18, s[8:9]
	v_cndmask_b32_e64 v141, v141, v143, s[8:9]
	v_cndmask_b32_e64 v20, v20, v22, s[10:11]
	v_cndmask_b32_e64 v145, v145, v147, s[10:11]
	v_cmp_gt_f32_e64 s[8:9], v20, v16
	s_nop 1
	v_cndmask_b32_e64 v16, v16, v20, s[8:9]
	v_cndmask_b32_e64 v141, v141, v145, s[8:9]
	v_mov_b32_e32 v129, v16
	v_add_u32_e32 v28, v57, v141
	ds_read_u8 v19, v28
	v_cmp_gt_u32_e64 s[62:63], 8, v141
	v_and_b32_e32 v29, 7, v141
	v_lshlrev_b32_e32 v29, 2, v29
	v_cndmask_b32_e64 v30, v25, v24, s[62:63]
	v_bfe_u32 v31, v30, v29, 4
	v_add_u32_e32 v52, v58, v31
	ds_read_u8 v21, v52
	v_lshl_add_u32 v27, v141, 2, v55
	ds_read_b32 v17, v27
	v_add_u32_e32 v53, 1, v31
	v_and_b32_e32 v27, 15, v53
	v_lshl_add_u32 v27, v27, 2, v56
	ds_read_b32 v18, v27
	v_cmp_gt_u32_e64 s[60:61], 15, v31
	v_lshlrev_b32_e64 v28, v29, 1
	s_nop 0
	v_cndmask_b32_e64 v28, 0, v28, s[60:61]
	v_cndmask_b32_e64 v30, 0, v28, s[62:63]
	v_sub_u32_e32 v28, v28, v30
	v_add_u32_e32 v24, v24, v30
	v_add_u32_e32 v25, v25, v28
	v_cmp_eq_u32_e64 s[8:9], 0, v141
	v_cmp_eq_u32_e64 s[10:11], 1, v141
	v_cmp_eq_u32_e64 s[12:13], 2, v141
	v_cmp_eq_u32_e64 s[24:25], 3, v141
	v_cmp_eq_u32_e64 s[26:27], 4, v141
	v_cmp_eq_u32_e64 s[28:29], 5, v141
	v_cmp_eq_u32_e64 s[30:31], 6, v141
	v_cmp_eq_u32_e64 s[34:35], 7, v141
	v_cmp_eq_u32_e64 s[36:37], 8, v141
	v_cmp_eq_u32_e64 s[38:39], 9, v141
	v_cmp_eq_u32_e64 s[40:41], 10, v141
	v_cmp_eq_u32_e64 s[42:43], 11, v141
	v_cmp_eq_u32_e64 s[44:45], 12, v141
	v_cmp_eq_u32_e64 s[46:47], 13, v141
	v_cmp_eq_u32_e64 s[60:61], 14, v141
	v_cmp_eq_u32_e64 s[62:63], 15, v141
	s_waitcnt lgkmcnt(0)
; DI void peer_topk_item(const Params& p, int tt128, int head, char* smem) {
;     ...
; #pragma unroll
;     for (int r = 0; r < 16; ++r) {
;       float best = cur[0]; int bi = 0; int bj = pp[0];
; #pragma unroll
;       for (int i = 1; i < 16; ++i) if (cur[i] > best) { best = cur[i]; bi = i; bj = pp[i]; }
;       sel[r] = best;
;       eid[r] = (int)ai[bi] * 128 + (int)bi_[bj];
;       const int nj = bj + 1;
;       const float nv = (nj < 16) ? (av[bi] + bv[nj & 15]) : -INFINITY;
; #pragma unroll
;       for (int i = 0; i < 16; ++i) { cur[i] = (i == bi) ? nv : cur[i]; pp[i] = (i == bi) ? nj : pp[i]; }
;     }
	v_cmp_gt_u32_e64 s[4:5], 16, v53
	v_add_f32_e32 v17, v17, v18
	v_lshl_add_u32 v37, v19, 7, v21
	v_cndmask_b32_e64 v17, v26, v17, s[4:5]
	v_cndmask_b32_e64 v0, v0, v17, s[8:9]
	v_cndmask_b32_e64 v1, v1, v17, s[10:11]
	v_cndmask_b32_e64 v2, v2, v17, s[12:13]
	v_cndmask_b32_e64 v3, v3, v17, s[24:25]
	v_cndmask_b32_e64 v4, v4, v17, s[26:27]
	v_cndmask_b32_e64 v5, v5, v17, s[28:29]
	v_cndmask_b32_e64 v6, v6, v17, s[30:31]
	v_cndmask_b32_e64 v7, v7, v17, s[34:35]
	v_cndmask_b32_e64 v8, v8, v17, s[36:37]
	v_cndmask_b32_e64 v9, v9, v17, s[38:39]
	v_cndmask_b32_e64 v10, v10, v17, s[40:41]
	v_cndmask_b32_e64 v11, v11, v17, s[42:43]
	v_cndmask_b32_e64 v12, v12, v17, s[44:45]
	v_cndmask_b32_e64 v13, v13, v17, s[46:47]
	v_cndmask_b32_e64 v14, v14, v17, s[60:61]
	v_cndmask_b32_e64 v15, v15, v17, s[62:63]
	v_cmp_gt_f32_e64 s[8:9], v1, v0
	v_cmp_gt_f32_e64 s[10:11], v3, v2
	v_cmp_gt_f32_e64 s[12:13], v5, v4
	v_cmp_gt_f32_e64 s[24:25], v7, v6
	v_cmp_gt_f32_e64 s[26:27], v9, v8
	v_cmp_gt_f32_e64 s[28:29], v11, v10
	v_cmp_gt_f32_e64 s[30:31], v13, v12
	v_cmp_gt_f32_e64 s[34:35], v15, v14
	v_cndmask_b32_e64 v16, v0, v1, s[8:9]
	v_cndmask_b32_e64 v141, 0, 1, s[8:9]
	v_cndmask_b32_e64 v17, v2, v3, s[10:11]
	v_cndmask_b32_e64 v142, 2, 3, s[10:11]
	v_cndmask_b32_e64 v18, v4, v5, s[12:13]
	v_cndmask_b32_e64 v143, 4, 5, s[12:13]
	v_cndmask_b32_e64 v19, v6, v7, s[24:25]
	v_cndmask_b32_e64 v144, 6, 7, s[24:25]
	v_cndmask_b32_e64 v20, v8, v9, s[26:27]
	v_cndmask_b32_e64 v145, 8, 9, s[26:27]
	v_cndmask_b32_e64 v21, v10, v11, s[28:29]
	v_cndmask_b32_e64 v146, 10, 11, s[28:29]
	v_cndmask_b32_e64 v22, v12, v13, s[30:31]
	v_cndmask_b32_e64 v147, 12, 13, s[30:31]
	v_cndmask_b32_e64 v23, v14, v15, s[34:35]
	v_cndmask_b32_e64 v148, 14, 15, s[34:35]
	v_cmp_gt_f32_e64 s[8:9], v17, v16
	v_cmp_gt_f32_e64 s[10:11], v19, v18
	v_cmp_gt_f32_e64 s[12:13], v21, v20
	v_cmp_gt_f32_e64 s[24:25], v23, v22
	v_cndmask_b32_e64 v16, v16, v17, s[8:9]
	v_cndmask_b32_e64 v141, v141, v142, s[8:9]
	v_cndmask_b32_e64 v18, v18, v19, s[10:11]
	v_cndmask_b32_e64 v143, v143, v144, s[10:11]
	v_cndmask_b32_e64 v20, v20, v21, s[12:13]
	v_cndmask_b32_e64 v145, v145, v146, s[12:13]
	v_cndmask_b32_e64 v22, v22, v23, s[24:25]
	v_cndmask_b32_e64 v147, v147, v148, s[24:25]
	v_cmp_gt_f32_e64 s[8:9], v18, v16
	v_cmp_gt_f32_e64 s[10:11], v22, v20
	s_nop 0
	v_cndmask_b32_e64 v16, v16, v18, s[8:9]
	v_cndmask_b32_e64 v141, v141, v143, s[8:9]
	v_cndmask_b32_e64 v20, v20, v22, s[10:11]
	v_cndmask_b32_e64 v145, v145, v147, s[10:11]
	v_cmp_gt_f32_e64 s[8:9], v20, v16
	s_nop 1
	v_cndmask_b32_e64 v16, v16, v20, s[8:9]
	v_cndmask_b32_e64 v141, v141, v145, s[8:9]
	v_mov_b32_e32 v130, v16
	v_add_u32_e32 v28, v57, v141
	ds_read_u8 v19, v28
	v_cmp_gt_u32_e64 s[62:63], 8, v141
	v_and_b32_e32 v29, 7, v141
	v_lshlrev_b32_e32 v29, 2, v29
	v_cndmask_b32_e64 v30, v25, v24, s[62:63]
	v_bfe_u32 v31, v30, v29, 4
	v_add_u32_e32 v52, v58, v31
	ds_read_u8 v21, v52
	v_lshl_add_u32 v27, v141, 2, v55
	ds_read_b32 v17, v27
	v_add_u32_e32 v53, 1, v31
	v_and_b32_e32 v27, 15, v53
	v_lshl_add_u32 v27, v27, 2, v56
	ds_read_b32 v18, v27
	v_cmp_gt_u32_e64 s[60:61], 15, v31
	v_lshlrev_b32_e64 v28, v29, 1
	s_nop 0
	v_cndmask_b32_e64 v28, 0, v28, s[60:61]
	v_cndmask_b32_e64 v30, 0, v28, s[62:63]
	v_sub_u32_e32 v28, v28, v30
	v_add_u32_e32 v24, v24, v30
	v_add_u32_e32 v25, v25, v28
	v_cmp_eq_u32_e64 s[8:9], 0, v141
	v_cmp_eq_u32_e64 s[10:11], 1, v141
	v_cmp_eq_u32_e64 s[12:13], 2, v141
	v_cmp_eq_u32_e64 s[24:25], 3, v141
	v_cmp_eq_u32_e64 s[26:27], 4, v141
	v_cmp_eq_u32_e64 s[28:29], 5, v141
	v_cmp_eq_u32_e64 s[30:31], 6, v141
	v_cmp_eq_u32_e64 s[34:35], 7, v141
	v_cmp_eq_u32_e64 s[36:37], 8, v141
	v_cmp_eq_u32_e64 s[38:39], 9, v141
	v_cmp_eq_u32_e64 s[40:41], 10, v141
	v_cmp_eq_u32_e64 s[42:43], 11, v141
	v_cmp_eq_u32_e64 s[44:45], 12, v141
	v_cmp_eq_u32_e64 s[46:47], 13, v141
	v_cmp_eq_u32_e64 s[60:61], 14, v141
	v_cmp_eq_u32_e64 s[62:63], 15, v141
	s_waitcnt lgkmcnt(0)
	v_cmp_gt_u32_e64 s[4:5], 16, v53
	v_add_f32_e32 v17, v17, v18
	v_lshl_add_u32 v38, v19, 7, v21
	v_cndmask_b32_e64 v17, v26, v17, s[4:5]
	v_cndmask_b32_e64 v0, v0, v17, s[8:9]
	v_cndmask_b32_e64 v1, v1, v17, s[10:11]
	v_cndmask_b32_e64 v2, v2, v17, s[12:13]
	v_cndmask_b32_e64 v3, v3, v17, s[24:25]
	v_cndmask_b32_e64 v4, v4, v17, s[26:27]
	v_cndmask_b32_e64 v5, v5, v17, s[28:29]
	v_cndmask_b32_e64 v6, v6, v17, s[30:31]
	v_cndmask_b32_e64 v7, v7, v17, s[34:35]
	v_cndmask_b32_e64 v8, v8, v17, s[36:37]
	v_cndmask_b32_e64 v9, v9, v17, s[38:39]
	v_cndmask_b32_e64 v10, v10, v17, s[40:41]
	v_cndmask_b32_e64 v11, v11, v17, s[42:43]
	v_cndmask_b32_e64 v12, v12, v17, s[44:45]
	v_cndmask_b32_e64 v13, v13, v17, s[46:47]
	v_cndmask_b32_e64 v14, v14, v17, s[60:61]
	v_cndmask_b32_e64 v15, v15, v17, s[62:63]
	v_cmp_gt_f32_e64 s[8:9], v1, v0
	v_cmp_gt_f32_e64 s[10:11], v3, v2
	v_cmp_gt_f32_e64 s[12:13], v5, v4
	v_cmp_gt_f32_e64 s[24:25], v7, v6
	v_cmp_gt_f32_e64 s[26:27], v9, v8
	v_cmp_gt_f32_e64 s[28:29], v11, v10
	v_cmp_gt_f32_e64 s[30:31], v13, v12
	v_cmp_gt_f32_e64 s[34:35], v15, v14
	v_cndmask_b32_e64 v16, v0, v1, s[8:9]
	v_cndmask_b32_e64 v141, 0, 1, s[8:9]
	v_cndmask_b32_e64 v17, v2, v3, s[10:11]
	v_cndmask_b32_e64 v142, 2, 3, s[10:11]
	v_cndmask_b32_e64 v18, v4, v5, s[12:13]
	v_cndmask_b32_e64 v143, 4, 5, s[12:13]
	v_cndmask_b32_e64 v19, v6, v7, s[24:25]
	v_cndmask_b32_e64 v144, 6, 7, s[24:25]
	v_cndmask_b32_e64 v20, v8, v9, s[26:27]
	v_cndmask_b32_e64 v145, 8, 9, s[26:27]
	v_cndmask_b32_e64 v21, v10, v11, s[28:29]
	v_cndmask_b32_e64 v146, 10, 11, s[28:29]
	v_cndmask_b32_e64 v22, v12, v13, s[30:31]
	v_cndmask_b32_e64 v147, 12, 13, s[30:31]
	v_cndmask_b32_e64 v23, v14, v15, s[34:35]
; DI void peer_topk_item(const Params& p, int tt128, int head, char* smem) {
;     ...
; #pragma unroll
;     for (int r = 0; r < 16; ++r) {
;       float best = cur[0]; int bi = 0; int bj = pp[0];
; #pragma unroll
;       for (int i = 1; i < 16; ++i) if (cur[i] > best) { best = cur[i]; bi = i; bj = pp[i]; }
;       sel[r] = best;
;       eid[r] = (int)ai[bi] * 128 + (int)bi_[bj];
;       const int nj = bj + 1;
;       const float nv = (nj < 16) ? (av[bi] + bv[nj & 15]) : -INFINITY;
; #pragma unroll
;       for (int i = 0; i < 16; ++i) { cur[i] = (i == bi) ? nv : cur[i]; pp[i] = (i == bi) ? nj : pp[i]; }
;     }
	v_cndmask_b32_e64 v148, 14, 15, s[34:35]
	v_cmp_gt_f32_e64 s[8:9], v17, v16
	v_cmp_gt_f32_e64 s[10:11], v19, v18
	v_cmp_gt_f32_e64 s[12:13], v21, v20
	v_cmp_gt_f32_e64 s[24:25], v23, v22
	v_cndmask_b32_e64 v16, v16, v17, s[8:9]
	v_cndmask_b32_e64 v141, v141, v142, s[8:9]
	v_cndmask_b32_e64 v18, v18, v19, s[10:11]
	v_cndmask_b32_e64 v143, v143, v144, s[10:11]
	v_cndmask_b32_e64 v20, v20, v21, s[12:13]
	v_cndmask_b32_e64 v145, v145, v146, s[12:13]
	v_cndmask_b32_e64 v22, v22, v23, s[24:25]
	v_cndmask_b32_e64 v147, v147, v148, s[24:25]
	v_cmp_gt_f32_e64 s[8:9], v18, v16
	v_cmp_gt_f32_e64 s[10:11], v22, v20
	s_nop 0
	v_cndmask_b32_e64 v16, v16, v18, s[8:9]
	v_cndmask_b32_e64 v141, v141, v143, s[8:9]
	v_cndmask_b32_e64 v20, v20, v22, s[10:11]
	v_cndmask_b32_e64 v145, v145, v147, s[10:11]
	v_cmp_gt_f32_e64 s[8:9], v20, v16
	s_nop 1
	v_cndmask_b32_e64 v16, v16, v20, s[8:9]
	v_cndmask_b32_e64 v141, v141, v145, s[8:9]
	v_mov_b32_e32 v131, v16
	v_add_u32_e32 v28, v57, v141
	ds_read_u8 v19, v28
	v_cmp_gt_u32_e64 s[62:63], 8, v141
	v_and_b32_e32 v29, 7, v141
	v_lshlrev_b32_e32 v29, 2, v29
	v_cndmask_b32_e64 v30, v25, v24, s[62:63]
	v_bfe_u32 v31, v30, v29, 4
	v_add_u32_e32 v52, v58, v31
	ds_read_u8 v21, v52
	v_lshl_add_u32 v27, v141, 2, v55
	ds_read_b32 v17, v27
	v_add_u32_e32 v53, 1, v31
	v_and_b32_e32 v27, 15, v53
	v_lshl_add_u32 v27, v27, 2, v56
	ds_read_b32 v18, v27
	v_cmp_gt_u32_e64 s[60:61], 15, v31
	v_lshlrev_b32_e64 v28, v29, 1
	s_nop 0
	v_cndmask_b32_e64 v28, 0, v28, s[60:61]
	v_cndmask_b32_e64 v30, 0, v28, s[62:63]
	v_sub_u32_e32 v28, v28, v30
	v_add_u32_e32 v24, v24, v30
	v_add_u32_e32 v25, v25, v28
	v_cmp_eq_u32_e64 s[8:9], 0, v141
	v_cmp_eq_u32_e64 s[10:11], 1, v141
	v_cmp_eq_u32_e64 s[12:13], 2, v141
	v_cmp_eq_u32_e64 s[24:25], 3, v141
	v_cmp_eq_u32_e64 s[26:27], 4, v141
	v_cmp_eq_u32_e64 s[28:29], 5, v141
	v_cmp_eq_u32_e64 s[30:31], 6, v141
	v_cmp_eq_u32_e64 s[34:35], 7, v141
	v_cmp_eq_u32_e64 s[36:37], 8, v141
	v_cmp_eq_u32_e64 s[38:39], 9, v141
	v_cmp_eq_u32_e64 s[40:41], 10, v141
	v_cmp_eq_u32_e64 s[42:43], 11, v141
	v_cmp_eq_u32_e64 s[44:45], 12, v141
	v_cmp_eq_u32_e64 s[46:47], 13, v141
	v_cmp_eq_u32_e64 s[60:61], 14, v141
	v_cmp_eq_u32_e64 s[62:63], 15, v141
	s_waitcnt lgkmcnt(0)
	v_cmp_gt_u32_e64 s[4:5], 16, v53
	v_add_f32_e32 v17, v17, v18
	v_lshl_add_u32 v39, v19, 7, v21
	v_cndmask_b32_e64 v17, v26, v17, s[4:5]
	v_cndmask_b32_e64 v0, v0, v17, s[8:9]
	v_cndmask_b32_e64 v1, v1, v17, s[10:11]
	v_cndmask_b32_e64 v2, v2, v17, s[12:13]
	v_cndmask_b32_e64 v3, v3, v17, s[24:25]
	v_cndmask_b32_e64 v4, v4, v17, s[26:27]
	v_cndmask_b32_e64 v5, v5, v17, s[28:29]
	v_cndmask_b32_e64 v6, v6, v17, s[30:31]
	v_cndmask_b32_e64 v7, v7, v17, s[34:35]
	v_cndmask_b32_e64 v8, v8, v17, s[36:37]
	v_cndmask_b32_e64 v9, v9, v17, s[38:39]
	v_cndmask_b32_e64 v10, v10, v17, s[40:41]
	v_cndmask_b32_e64 v11, v11, v17, s[42:43]
	v_cndmask_b32_e64 v12, v12, v17, s[44:45]
	v_cndmask_b32_e64 v13, v13, v17, s[46:47]
	v_cndmask_b32_e64 v14, v14, v17, s[60:61]
	v_cndmask_b32_e64 v15, v15, v17, s[62:63]
	v_cmp_gt_f32_e64 s[8:9], v1, v0
	v_cmp_gt_f32_e64 s[10:11], v3, v2
	v_cmp_gt_f32_e64 s[12:13], v5, v4
	v_cmp_gt_f32_e64 s[24:25], v7, v6
	v_cmp_gt_f32_e64 s[26:27], v9, v8
	v_cmp_gt_f32_e64 s[28:29], v11, v10
	v_cmp_gt_f32_e64 s[30:31], v13, v12
	v_cmp_gt_f32_e64 s[34:35], v15, v14
	v_cndmask_b32_e64 v16, v0, v1, s[8:9]
	v_cndmask_b32_e64 v141, 0, 1, s[8:9]
	v_cndmask_b32_e64 v17, v2, v3, s[10:11]
	v_cndmask_b32_e64 v142, 2, 3, s[10:11]
	v_cndmask_b32_e64 v18, v4, v5, s[12:13]
	v_cndmask_b32_e64 v143, 4, 5, s[12:13]
	v_cndmask_b32_e64 v19, v6, v7, s[24:25]
	v_cndmask_b32_e64 v144, 6, 7, s[24:25]
	v_cndmask_b32_e64 v20, v8, v9, s[26:27]
	v_cndmask_b32_e64 v145, 8, 9, s[26:27]
	v_cndmask_b32_e64 v21, v10, v11, s[28:29]
	v_cndmask_b32_e64 v146, 10, 11, s[28:29]
	v_cndmask_b32_e64 v22, v12, v13, s[30:31]
	v_cndmask_b32_e64 v147, 12, 13, s[30:31]
	v_cndmask_b32_e64 v23, v14, v15, s[34:35]
	v_cndmask_b32_e64 v148, 14, 15, s[34:35]
	v_cmp_gt_f32_e64 s[8:9], v17, v16
	v_cmp_gt_f32_e64 s[10:11], v19, v18
	v_cmp_gt_f32_e64 s[12:13], v21, v20
	v_cmp_gt_f32_e64 s[24:25], v23, v22
	v_cndmask_b32_e64 v16, v16, v17, s[8:9]
	v_cndmask_b32_e64 v141, v141, v142, s[8:9]
	v_cndmask_b32_e64 v18, v18, v19, s[10:11]
	v_cndmask_b32_e64 v143, v143, v144, s[10:11]
	v_cndmask_b32_e64 v20, v20, v21, s[12:13]
	v_cndmask_b32_e64 v145, v145, v146, s[12:13]
	v_cndmask_b32_e64 v22, v22, v23, s[24:25]
	v_cndmask_b32_e64 v147, v147, v148, s[24:25]
	v_cmp_gt_f32_e64 s[8:9], v18, v16
	v_cmp_gt_f32_e64 s[10:11], v22, v20
	s_nop 0
	v_cndmask_b32_e64 v16, v16, v18, s[8:9]
	v_cndmask_b32_e64 v141, v141, v143, s[8:9]
	v_cndmask_b32_e64 v20, v20, v22, s[10:11]
	v_cndmask_b32_e64 v145, v145, v147, s[10:11]
	v_cmp_gt_f32_e64 s[8:9], v20, v16
	s_nop 1
	v_cndmask_b32_e64 v16, v16, v20, s[8:9]
	v_cndmask_b32_e64 v141, v141, v145, s[8:9]
	v_mov_b32_e32 v132, v16
	v_add_u32_e32 v28, v57, v141
	ds_read_u8 v19, v28
	v_cmp_gt_u32_e64 s[62:63], 8, v141
	v_and_b32_e32 v29, 7, v141
	v_lshlrev_b32_e32 v29, 2, v29
	v_cndmask_b32_e64 v30, v25, v24, s[62:63]
	v_bfe_u32 v31, v30, v29, 4
	v_add_u32_e32 v52, v58, v31
	ds_read_u8 v21, v52
	v_lshl_add_u32 v27, v141, 2, v55
	ds_read_b32 v17, v27
	v_add_u32_e32 v53, 1, v31
	v_and_b32_e32 v27, 15, v53
	v_lshl_add_u32 v27, v27, 2, v56
	ds_read_b32 v18, v27
	v_cmp_gt_u32_e64 s[60:61], 15, v31
	v_lshlrev_b32_e64 v28, v29, 1
	s_nop 0
	v_cndmask_b32_e64 v28, 0, v28, s[60:61]
	v_cndmask_b32_e64 v30, 0, v28, s[62:63]
	v_sub_u32_e32 v28, v28, v30
	v_add_u32_e32 v24, v24, v30
	v_add_u32_e32 v25, v25, v28
	v_cmp_eq_u32_e64 s[8:9], 0, v141
	v_cmp_eq_u32_e64 s[10:11], 1, v141
	v_cmp_eq_u32_e64 s[12:13], 2, v141
	v_cmp_eq_u32_e64 s[24:25], 3, v141
	v_cmp_eq_u32_e64 s[26:27], 4, v141
	v_cmp_eq_u32_e64 s[28:29], 5, v141
	v_cmp_eq_u32_e64 s[30:31], 6, v141
	v_cmp_eq_u32_e64 s[34:35], 7, v141
	v_cmp_eq_u32_e64 s[36:37], 8, v141
	v_cmp_eq_u32_e64 s[38:39], 9, v141
	v_cmp_eq_u32_e64 s[40:41], 10, v141
	v_cmp_eq_u32_e64 s[42:43], 11, v141
	v_cmp_eq_u32_e64 s[44:45], 12, v141
	v_cmp_eq_u32_e64 s[46:47], 13, v141
	v_cmp_eq_u32_e64 s[60:61], 14, v141
	v_cmp_eq_u32_e64 s[62:63], 15, v141
	s_waitcnt lgkmcnt(0)
; DI void peer_topk_item(const Params& p, int tt128, int head, char* smem) {
;     ...
; #pragma unroll
;     for (int r = 0; r < 16; ++r) {
;       float best = cur[0]; int bi = 0; int bj = pp[0];
; #pragma unroll
;       for (int i = 1; i < 16; ++i) if (cur[i] > best) { best = cur[i]; bi = i; bj = pp[i]; }
;       sel[r] = best;
;       eid[r] = (int)ai[bi] * 128 + (int)bi_[bj];
;       const int nj = bj + 1;
;       const float nv = (nj < 16) ? (av[bi] + bv[nj & 15]) : -INFINITY;
; #pragma unroll
;       for (int i = 0; i < 16; ++i) { cur[i] = (i == bi) ? nv : cur[i]; pp[i] = (i == bi) ? nj : pp[i]; }
;     }
	v_cmp_gt_u32_e64 s[4:5], 16, v53
	v_add_f32_e32 v17, v17, v18
	v_lshl_add_u32 v40, v19, 7, v21
	v_cndmask_b32_e64 v17, v26, v17, s[4:5]
	v_cndmask_b32_e64 v0, v0, v17, s[8:9]
	v_cndmask_b32_e64 v1, v1, v17, s[10:11]
	v_cndmask_b32_e64 v2, v2, v17, s[12:13]
	v_cndmask_b32_e64 v3, v3, v17, s[24:25]
	v_cndmask_b32_e64 v4, v4, v17, s[26:27]
	v_cndmask_b32_e64 v5, v5, v17, s[28:29]
	v_cndmask_b32_e64 v6, v6, v17, s[30:31]
	v_cndmask_b32_e64 v7, v7, v17, s[34:35]
	v_cndmask_b32_e64 v8, v8, v17, s[36:37]
	v_cndmask_b32_e64 v9, v9, v17, s[38:39]
	v_cndmask_b32_e64 v10, v10, v17, s[40:41]
	v_cndmask_b32_e64 v11, v11, v17, s[42:43]
	v_cndmask_b32_e64 v12, v12, v17, s[44:45]
	v_cndmask_b32_e64 v13, v13, v17, s[46:47]
	v_cndmask_b32_e64 v14, v14, v17, s[60:61]
	v_cndmask_b32_e64 v15, v15, v17, s[62:63]
	v_cmp_gt_f32_e64 s[8:9], v1, v0
	v_cmp_gt_f32_e64 s[10:11], v3, v2
	v_cmp_gt_f32_e64 s[12:13], v5, v4
	v_cmp_gt_f32_e64 s[24:25], v7, v6
	v_cmp_gt_f32_e64 s[26:27], v9, v8
	v_cmp_gt_f32_e64 s[28:29], v11, v10
	v_cmp_gt_f32_e64 s[30:31], v13, v12
	v_cmp_gt_f32_e64 s[34:35], v15, v14
	v_cndmask_b32_e64 v16, v0, v1, s[8:9]
	v_cndmask_b32_e64 v141, 0, 1, s[8:9]
	v_cndmask_b32_e64 v17, v2, v3, s[10:11]
	v_cndmask_b32_e64 v142, 2, 3, s[10:11]
	v_cndmask_b32_e64 v18, v4, v5, s[12:13]
	v_cndmask_b32_e64 v143, 4, 5, s[12:13]
	v_cndmask_b32_e64 v19, v6, v7, s[24:25]
	v_cndmask_b32_e64 v144, 6, 7, s[24:25]
	v_cndmask_b32_e64 v20, v8, v9, s[26:27]
	v_cndmask_b32_e64 v145, 8, 9, s[26:27]
	v_cndmask_b32_e64 v21, v10, v11, s[28:29]
	v_cndmask_b32_e64 v146, 10, 11, s[28:29]
	v_cndmask_b32_e64 v22, v12, v13, s[30:31]
	v_cndmask_b32_e64 v147, 12, 13, s[30:31]
	v_cndmask_b32_e64 v23, v14, v15, s[34:35]
	v_cndmask_b32_e64 v148, 14, 15, s[34:35]
	v_cmp_gt_f32_e64 s[8:9], v17, v16
	v_cmp_gt_f32_e64 s[10:11], v19, v18
	v_cmp_gt_f32_e64 s[12:13], v21, v20
	v_cmp_gt_f32_e64 s[24:25], v23, v22
	v_cndmask_b32_e64 v16, v16, v17, s[8:9]
	v_cndmask_b32_e64 v141, v141, v142, s[8:9]
	v_cndmask_b32_e64 v18, v18, v19, s[10:11]
	v_cndmask_b32_e64 v143, v143, v144, s[10:11]
	v_cndmask_b32_e64 v20, v20, v21, s[12:13]
	v_cndmask_b32_e64 v145, v145, v146, s[12:13]
	v_cndmask_b32_e64 v22, v22, v23, s[24:25]
	v_cndmask_b32_e64 v147, v147, v148, s[24:25]
	v_cmp_gt_f32_e64 s[8:9], v18, v16
	v_cmp_gt_f32_e64 s[10:11], v22, v20
	s_nop 0
	v_cndmask_b32_e64 v16, v16, v18, s[8:9]
	v_cndmask_b32_e64 v141, v141, v143, s[8:9]
	v_cndmask_b32_e64 v20, v20, v22, s[10:11]
	v_cndmask_b32_e64 v145, v145, v147, s[10:11]
	v_cmp_gt_f32_e64 s[8:9], v20, v16
	s_nop 1
	v_cndmask_b32_e64 v16, v16, v20, s[8:9]
	v_cndmask_b32_e64 v141, v141, v145, s[8:9]
	v_mov_b32_e32 v133, v16
	v_add_u32_e32 v28, v57, v141
	ds_read_u8 v19, v28
	v_cmp_gt_u32_e64 s[62:63], 8, v141
	v_and_b32_e32 v29, 7, v141
	v_lshlrev_b32_e32 v29, 2, v29
	v_cndmask_b32_e64 v30, v25, v24, s[62:63]
	v_bfe_u32 v31, v30, v29, 4
	v_add_u32_e32 v52, v58, v31
	ds_read_u8 v21, v52
	v_lshl_add_u32 v27, v141, 2, v55
	ds_read_b32 v17, v27
	v_add_u32_e32 v53, 1, v31
	v_and_b32_e32 v27, 15, v53
	v_lshl_add_u32 v27, v27, 2, v56
	ds_read_b32 v18, v27
	v_cmp_gt_u32_e64 s[60:61], 15, v31
	v_lshlrev_b32_e64 v28, v29, 1
	s_nop 0
	v_cndmask_b32_e64 v28, 0, v28, s[60:61]
	v_cndmask_b32_e64 v30, 0, v28, s[62:63]
	v_sub_u32_e32 v28, v28, v30
	v_add_u32_e32 v24, v24, v30
	v_add_u32_e32 v25, v25, v28
	v_cmp_eq_u32_e64 s[8:9], 0, v141
	v_cmp_eq_u32_e64 s[10:11], 1, v141
	v_cmp_eq_u32_e64 s[12:13], 2, v141
	v_cmp_eq_u32_e64 s[24:25], 3, v141
	v_cmp_eq_u32_e64 s[26:27], 4, v141
	v_cmp_eq_u32_e64 s[28:29], 5, v141
	v_cmp_eq_u32_e64 s[30:31], 6, v141
	v_cmp_eq_u32_e64 s[34:35], 7, v141
	v_cmp_eq_u32_e64 s[36:37], 8, v141
	v_cmp_eq_u32_e64 s[38:39], 9, v141
	v_cmp_eq_u32_e64 s[40:41], 10, v141
	v_cmp_eq_u32_e64 s[42:43], 11, v141
	v_cmp_eq_u32_e64 s[44:45], 12, v141
	v_cmp_eq_u32_e64 s[46:47], 13, v141
	v_cmp_eq_u32_e64 s[60:61], 14, v141
	v_cmp_eq_u32_e64 s[62:63], 15, v141
	s_waitcnt lgkmcnt(0)
	v_cmp_gt_u32_e64 s[4:5], 16, v53
	v_add_f32_e32 v17, v17, v18
	v_lshl_add_u32 v41, v19, 7, v21
	v_cndmask_b32_e64 v17, v26, v17, s[4:5]
	v_cndmask_b32_e64 v0, v0, v17, s[8:9]
	v_cndmask_b32_e64 v1, v1, v17, s[10:11]
	v_cndmask_b32_e64 v2, v2, v17, s[12:13]
	v_cndmask_b32_e64 v3, v3, v17, s[24:25]
	v_cndmask_b32_e64 v4, v4, v17, s[26:27]
	v_cndmask_b32_e64 v5, v5, v17, s[28:29]
	v_cndmask_b32_e64 v6, v6, v17, s[30:31]
	v_cndmask_b32_e64 v7, v7, v17, s[34:35]
	v_cndmask_b32_e64 v8, v8, v17, s[36:37]
	v_cndmask_b32_e64 v9, v9, v17, s[38:39]
	v_cndmask_b32_e64 v10, v10, v17, s[40:41]
	v_cndmask_b32_e64 v11, v11, v17, s[42:43]
	v_cndmask_b32_e64 v12, v12, v17, s[44:45]
	v_cndmask_b32_e64 v13, v13, v17, s[46:47]
	v_cndmask_b32_e64 v14, v14, v17, s[60:61]
	v_cndmask_b32_e64 v15, v15, v17, s[62:63]
	v_cmp_gt_f32_e64 s[8:9], v1, v0
	v_cmp_gt_f32_e64 s[10:11], v3, v2
	v_cmp_gt_f32_e64 s[12:13], v5, v4
	v_cmp_gt_f32_e64 s[24:25], v7, v6
	v_cmp_gt_f32_e64 s[26:27], v9, v8
	v_cmp_gt_f32_e64 s[28:29], v11, v10
	v_cmp_gt_f32_e64 s[30:31], v13, v12
	v_cmp_gt_f32_e64 s[34:35], v15, v14
	v_cndmask_b32_e64 v16, v0, v1, s[8:9]
	v_cndmask_b32_e64 v141, 0, 1, s[8:9]
	v_cndmask_b32_e64 v17, v2, v3, s[10:11]
	v_cndmask_b32_e64 v142, 2, 3, s[10:11]
	v_cndmask_b32_e64 v18, v4, v5, s[12:13]
	v_cndmask_b32_e64 v143, 4, 5, s[12:13]
	v_cndmask_b32_e64 v19, v6, v7, s[24:25]
	v_cndmask_b32_e64 v144, 6, 7, s[24:25]
	v_cndmask_b32_e64 v20, v8, v9, s[26:27]
	v_cndmask_b32_e64 v145, 8, 9, s[26:27]
	v_cndmask_b32_e64 v21, v10, v11, s[28:29]
	v_cndmask_b32_e64 v146, 10, 11, s[28:29]
	v_cndmask_b32_e64 v22, v12, v13, s[30:31]
	v_cndmask_b32_e64 v147, 12, 13, s[30:31]
	v_cndmask_b32_e64 v23, v14, v15, s[34:35]
; DI void peer_topk_item(const Params& p, int tt128, int head, char* smem) {
;     ...
; #pragma unroll
;     for (int r = 0; r < 16; ++r) {
;       float best = cur[0]; int bi = 0; int bj = pp[0];
; #pragma unroll
;       for (int i = 1; i < 16; ++i) if (cur[i] > best) { best = cur[i]; bi = i; bj = pp[i]; }
;       sel[r] = best;
;       eid[r] = (int)ai[bi] * 128 + (int)bi_[bj];
;       const int nj = bj + 1;
;       const float nv = (nj < 16) ? (av[bi] + bv[nj & 15]) : -INFINITY;
; #pragma unroll
;       for (int i = 0; i < 16; ++i) { cur[i] = (i == bi) ? nv : cur[i]; pp[i] = (i == bi) ? nj : pp[i]; }
;     }
	v_cndmask_b32_e64 v148, 14, 15, s[34:35]
	v_cmp_gt_f32_e64 s[8:9], v17, v16
	v_cmp_gt_f32_e64 s[10:11], v19, v18
	v_cmp_gt_f32_e64 s[12:13], v21, v20
	v_cmp_gt_f32_e64 s[24:25], v23, v22
	v_cndmask_b32_e64 v16, v16, v17, s[8:9]
	v_cndmask_b32_e64 v141, v141, v142, s[8:9]
	v_cndmask_b32_e64 v18, v18, v19, s[10:11]
	v_cndmask_b32_e64 v143, v143, v144, s[10:11]
	v_cndmask_b32_e64 v20, v20, v21, s[12:13]
	v_cndmask_b32_e64 v145, v145, v146, s[12:13]
	v_cndmask_b32_e64 v22, v22, v23, s[24:25]
	v_cndmask_b32_e64 v147, v147, v148, s[24:25]
	v_cmp_gt_f32_e64 s[8:9], v18, v16
	v_cmp_gt_f32_e64 s[10:11], v22, v20
	s_nop 0
	v_cndmask_b32_e64 v16, v16, v18, s[8:9]
	v_cndmask_b32_e64 v141, v141, v143, s[8:9]
	v_cndmask_b32_e64 v20, v20, v22, s[10:11]
	v_cndmask_b32_e64 v145, v145, v147, s[10:11]
	v_cmp_gt_f32_e64 s[8:9], v20, v16
	s_nop 1
	v_cndmask_b32_e64 v16, v16, v20, s[8:9]
	v_cndmask_b32_e64 v141, v141, v145, s[8:9]
	v_mov_b32_e32 v134, v16
	v_add_u32_e32 v28, v57, v141
	ds_read_u8 v19, v28
	v_cmp_gt_u32_e64 s[62:63], 8, v141
	v_and_b32_e32 v29, 7, v141
	v_lshlrev_b32_e32 v29, 2, v29
	v_cndmask_b32_e64 v30, v25, v24, s[62:63]
	v_bfe_u32 v31, v30, v29, 4
	v_add_u32_e32 v52, v58, v31
	ds_read_u8 v21, v52
	v_lshl_add_u32 v27, v141, 2, v55
	ds_read_b32 v17, v27
	v_add_u32_e32 v53, 1, v31
	v_and_b32_e32 v27, 15, v53
	v_lshl_add_u32 v27, v27, 2, v56
	ds_read_b32 v18, v27
	v_cmp_gt_u32_e64 s[60:61], 15, v31
	v_lshlrev_b32_e64 v28, v29, 1
	s_nop 0
	v_cndmask_b32_e64 v28, 0, v28, s[60:61]
	v_cndmask_b32_e64 v30, 0, v28, s[62:63]
	v_sub_u32_e32 v28, v28, v30
	v_add_u32_e32 v24, v24, v30
	v_add_u32_e32 v25, v25, v28
	v_cmp_eq_u32_e64 s[8:9], 0, v141
	v_cmp_eq_u32_e64 s[10:11], 1, v141
	v_cmp_eq_u32_e64 s[12:13], 2, v141
	v_cmp_eq_u32_e64 s[24:25], 3, v141
	v_cmp_eq_u32_e64 s[26:27], 4, v141
	v_cmp_eq_u32_e64 s[28:29], 5, v141
	v_cmp_eq_u32_e64 s[30:31], 6, v141
	v_cmp_eq_u32_e64 s[34:35], 7, v141
	v_cmp_eq_u32_e64 s[36:37], 8, v141
	v_cmp_eq_u32_e64 s[38:39], 9, v141
	v_cmp_eq_u32_e64 s[40:41], 10, v141
	v_cmp_eq_u32_e64 s[42:43], 11, v141
	v_cmp_eq_u32_e64 s[44:45], 12, v141
	v_cmp_eq_u32_e64 s[46:47], 13, v141
	v_cmp_eq_u32_e64 s[60:61], 14, v141
	v_cmp_eq_u32_e64 s[62:63], 15, v141
	s_waitcnt lgkmcnt(0)
	v_cmp_gt_u32_e64 s[4:5], 16, v53
	v_add_f32_e32 v17, v17, v18
	v_lshl_add_u32 v42, v19, 7, v21
	v_cndmask_b32_e64 v17, v26, v17, s[4:5]
	v_cndmask_b32_e64 v0, v0, v17, s[8:9]
	v_cndmask_b32_e64 v1, v1, v17, s[10:11]
	v_cndmask_b32_e64 v2, v2, v17, s[12:13]
	v_cndmask_b32_e64 v3, v3, v17, s[24:25]
	v_cndmask_b32_e64 v4, v4, v17, s[26:27]
	v_cndmask_b32_e64 v5, v5, v17, s[28:29]
	v_cndmask_b32_e64 v6, v6, v17, s[30:31]
	v_cndmask_b32_e64 v7, v7, v17, s[34:35]
	v_cndmask_b32_e64 v8, v8, v17, s[36:37]
	v_cndmask_b32_e64 v9, v9, v17, s[38:39]
	v_cndmask_b32_e64 v10, v10, v17, s[40:41]
	v_cndmask_b32_e64 v11, v11, v17, s[42:43]
	v_cndmask_b32_e64 v12, v12, v17, s[44:45]
	v_cndmask_b32_e64 v13, v13, v17, s[46:47]
	v_cndmask_b32_e64 v14, v14, v17, s[60:61]
	v_cndmask_b32_e64 v15, v15, v17, s[62:63]
	v_cmp_gt_f32_e64 s[8:9], v1, v0
	v_cmp_gt_f32_e64 s[10:11], v3, v2
	v_cmp_gt_f32_e64 s[12:13], v5, v4
	v_cmp_gt_f32_e64 s[24:25], v7, v6
	v_cmp_gt_f32_e64 s[26:27], v9, v8
	v_cmp_gt_f32_e64 s[28:29], v11, v10
	v_cmp_gt_f32_e64 s[30:31], v13, v12
	v_cmp_gt_f32_e64 s[34:35], v15, v14
	v_cndmask_b32_e64 v16, v0, v1, s[8:9]
	v_cndmask_b32_e64 v141, 0, 1, s[8:9]
	v_cndmask_b32_e64 v17, v2, v3, s[10:11]
	v_cndmask_b32_e64 v142, 2, 3, s[10:11]
	v_cndmask_b32_e64 v18, v4, v5, s[12:13]
	v_cndmask_b32_e64 v143, 4, 5, s[12:13]
	v_cndmask_b32_e64 v19, v6, v7, s[24:25]
	v_cndmask_b32_e64 v144, 6, 7, s[24:25]
	v_cndmask_b32_e64 v20, v8, v9, s[26:27]
	v_cndmask_b32_e64 v145, 8, 9, s[26:27]
	v_cndmask_b32_e64 v21, v10, v11, s[28:29]
	v_cndmask_b32_e64 v146, 10, 11, s[28:29]
	v_cndmask_b32_e64 v22, v12, v13, s[30:31]
	v_cndmask_b32_e64 v147, 12, 13, s[30:31]
	v_cndmask_b32_e64 v23, v14, v15, s[34:35]
	v_cndmask_b32_e64 v148, 14, 15, s[34:35]
	v_cmp_gt_f32_e64 s[8:9], v17, v16
	v_cmp_gt_f32_e64 s[10:11], v19, v18
	v_cmp_gt_f32_e64 s[12:13], v21, v20
	v_cmp_gt_f32_e64 s[24:25], v23, v22
	v_cndmask_b32_e64 v16, v16, v17, s[8:9]
	v_cndmask_b32_e64 v141, v141, v142, s[8:9]
	v_cndmask_b32_e64 v18, v18, v19, s[10:11]
	v_cndmask_b32_e64 v143, v143, v144, s[10:11]
	v_cndmask_b32_e64 v20, v20, v21, s[12:13]
	v_cndmask_b32_e64 v145, v145, v146, s[12:13]
	v_cndmask_b32_e64 v22, v22, v23, s[24:25]
	v_cndmask_b32_e64 v147, v147, v148, s[24:25]
	v_cmp_gt_f32_e64 s[8:9], v18, v16
	v_cmp_gt_f32_e64 s[10:11], v22, v20
	s_nop 0
	v_cndmask_b32_e64 v16, v16, v18, s[8:9]
	v_cndmask_b32_e64 v141, v141, v143, s[8:9]
	v_cndmask_b32_e64 v20, v20, v22, s[10:11]
	v_cndmask_b32_e64 v145, v145, v147, s[10:11]
	v_cmp_gt_f32_e64 s[8:9], v20, v16
	s_nop 1
	v_cndmask_b32_e64 v16, v16, v20, s[8:9]
	v_cndmask_b32_e64 v141, v141, v145, s[8:9]
	v_mov_b32_e32 v135, v16
	v_add_u32_e32 v28, v57, v141
	ds_read_u8 v19, v28
	v_cmp_gt_u32_e64 s[62:63], 8, v141
	v_and_b32_e32 v29, 7, v141
	v_lshlrev_b32_e32 v29, 2, v29
	v_cndmask_b32_e64 v30, v25, v24, s[62:63]
	v_bfe_u32 v31, v30, v29, 4
	v_add_u32_e32 v52, v58, v31
	ds_read_u8 v21, v52
	v_lshl_add_u32 v27, v141, 2, v55
	ds_read_b32 v17, v27
	v_add_u32_e32 v53, 1, v31
	v_and_b32_e32 v27, 15, v53
	v_lshl_add_u32 v27, v27, 2, v56
	ds_read_b32 v18, v27
	v_cmp_gt_u32_e64 s[60:61], 15, v31
	v_lshlrev_b32_e64 v28, v29, 1
	s_nop 0
	v_cndmask_b32_e64 v28, 0, v28, s[60:61]
	v_cndmask_b32_e64 v30, 0, v28, s[62:63]
	v_sub_u32_e32 v28, v28, v30
	v_add_u32_e32 v24, v24, v30
	v_add_u32_e32 v25, v25, v28
	v_cmp_eq_u32_e64 s[8:9], 0, v141
	v_cmp_eq_u32_e64 s[10:11], 1, v141
	v_cmp_eq_u32_e64 s[12:13], 2, v141
	v_cmp_eq_u32_e64 s[24:25], 3, v141
	v_cmp_eq_u32_e64 s[26:27], 4, v141
	v_cmp_eq_u32_e64 s[28:29], 5, v141
	v_cmp_eq_u32_e64 s[30:31], 6, v141
	v_cmp_eq_u32_e64 s[34:35], 7, v141
	v_cmp_eq_u32_e64 s[36:37], 8, v141
	v_cmp_eq_u32_e64 s[38:39], 9, v141
	v_cmp_eq_u32_e64 s[40:41], 10, v141
	v_cmp_eq_u32_e64 s[42:43], 11, v141
	v_cmp_eq_u32_e64 s[44:45], 12, v141
	v_cmp_eq_u32_e64 s[46:47], 13, v141
	v_cmp_eq_u32_e64 s[60:61], 14, v141
	v_cmp_eq_u32_e64 s[62:63], 15, v141
	s_waitcnt lgkmcnt(0)
; DI void peer_topk_item(const Params& p, int tt128, int head, char* smem) {
;     ...
; #pragma unroll
;     for (int r = 0; r < 16; ++r) {
;       float best = cur[0]; int bi = 0; int bj = pp[0];
; #pragma unroll
;       for (int i = 1; i < 16; ++i) if (cur[i] > best) { best = cur[i]; bi = i; bj = pp[i]; }
;       sel[r] = best;
;       eid[r] = (int)ai[bi] * 128 + (int)bi_[bj];
;       const int nj = bj + 1;
;       const float nv = (nj < 16) ? (av[bi] + bv[nj & 15]) : -INFINITY;
; #pragma unroll
;       for (int i = 0; i < 16; ++i) { cur[i] = (i == bi) ? nv : cur[i]; pp[i] = (i == bi) ? nj : pp[i]; }
;     }
	v_cmp_gt_u32_e64 s[4:5], 16, v53
	v_add_f32_e32 v17, v17, v18
	v_lshl_add_u32 v43, v19, 7, v21
	v_cndmask_b32_e64 v17, v26, v17, s[4:5]
	v_cndmask_b32_e64 v0, v0, v17, s[8:9]
	v_cndmask_b32_e64 v1, v1, v17, s[10:11]
	v_cndmask_b32_e64 v2, v2, v17, s[12:13]
	v_cndmask_b32_e64 v3, v3, v17, s[24:25]
	v_cndmask_b32_e64 v4, v4, v17, s[26:27]
	v_cndmask_b32_e64 v5, v5, v17, s[28:29]
	v_cndmask_b32_e64 v6, v6, v17, s[30:31]
	v_cndmask_b32_e64 v7, v7, v17, s[34:35]
	v_cndmask_b32_e64 v8, v8, v17, s[36:37]
	v_cndmask_b32_e64 v9, v9, v17, s[38:39]
	v_cndmask_b32_e64 v10, v10, v17, s[40:41]
	v_cndmask_b32_e64 v11, v11, v17, s[42:43]
	v_cndmask_b32_e64 v12, v12, v17, s[44:45]
	v_cndmask_b32_e64 v13, v13, v17, s[46:47]
	v_cndmask_b32_e64 v14, v14, v17, s[60:61]
	v_cndmask_b32_e64 v15, v15, v17, s[62:63]
	v_cmp_gt_f32_e64 s[8:9], v1, v0
	v_cmp_gt_f32_e64 s[10:11], v3, v2
	v_cmp_gt_f32_e64 s[12:13], v5, v4
	v_cmp_gt_f32_e64 s[24:25], v7, v6
	v_cmp_gt_f32_e64 s[26:27], v9, v8
	v_cmp_gt_f32_e64 s[28:29], v11, v10
	v_cmp_gt_f32_e64 s[30:31], v13, v12
	v_cmp_gt_f32_e64 s[34:35], v15, v14
	v_cndmask_b32_e64 v16, v0, v1, s[8:9]
	v_cndmask_b32_e64 v141, 0, 1, s[8:9]
	v_cndmask_b32_e64 v17, v2, v3, s[10:11]
	v_cndmask_b32_e64 v142, 2, 3, s[10:11]
	v_cndmask_b32_e64 v18, v4, v5, s[12:13]
	v_cndmask_b32_e64 v143, 4, 5, s[12:13]
	v_cndmask_b32_e64 v19, v6, v7, s[24:25]
	v_cndmask_b32_e64 v144, 6, 7, s[24:25]
	v_cndmask_b32_e64 v20, v8, v9, s[26:27]
	v_cndmask_b32_e64 v145, 8, 9, s[26:27]
	v_cndmask_b32_e64 v21, v10, v11, s[28:29]
	v_cndmask_b32_e64 v146, 10, 11, s[28:29]
	v_cndmask_b32_e64 v22, v12, v13, s[30:31]
	v_cndmask_b32_e64 v147, 12, 13, s[30:31]
	v_cndmask_b32_e64 v23, v14, v15, s[34:35]
	v_cndmask_b32_e64 v148, 14, 15, s[34:35]
	v_cmp_gt_f32_e64 s[8:9], v17, v16
	v_cmp_gt_f32_e64 s[10:11], v19, v18
	v_cmp_gt_f32_e64 s[12:13], v21, v20
	v_cmp_gt_f32_e64 s[24:25], v23, v22
	v_cndmask_b32_e64 v16, v16, v17, s[8:9]
	v_cndmask_b32_e64 v141, v141, v142, s[8:9]
	v_cndmask_b32_e64 v18, v18, v19, s[10:11]
	v_cndmask_b32_e64 v143, v143, v144, s[10:11]
	v_cndmask_b32_e64 v20, v20, v21, s[12:13]
	v_cndmask_b32_e64 v145, v145, v146, s[12:13]
	v_cndmask_b32_e64 v22, v22, v23, s[24:25]
	v_cndmask_b32_e64 v147, v147, v148, s[24:25]
	v_cmp_gt_f32_e64 s[8:9], v18, v16
	v_cmp_gt_f32_e64 s[10:11], v22, v20
	s_nop 0
	v_cndmask_b32_e64 v16, v16, v18, s[8:9]
	v_cndmask_b32_e64 v141, v141, v143, s[8:9]
	v_cndmask_b32_e64 v20, v20, v22, s[10:11]
	v_cndmask_b32_e64 v145, v145, v147, s[10:11]
	v_cmp_gt_f32_e64 s[8:9], v20, v16
	s_nop 1
	v_cndmask_b32_e64 v16, v16, v20, s[8:9]
	v_cndmask_b32_e64 v141, v141, v145, s[8:9]
	v_mov_b32_e32 v136, v16
	v_add_u32_e32 v28, v57, v141
	ds_read_u8 v19, v28
	v_cmp_gt_u32_e64 s[62:63], 8, v141
	v_and_b32_e32 v29, 7, v141
	v_lshlrev_b32_e32 v29, 2, v29
	v_cndmask_b32_e64 v30, v25, v24, s[62:63]
	v_bfe_u32 v31, v30, v29, 4
	v_add_u32_e32 v52, v58, v31
	ds_read_u8 v21, v52
	v_lshl_add_u32 v27, v141, 2, v55
	ds_read_b32 v17, v27
	v_add_u32_e32 v53, 1, v31
	v_and_b32_e32 v27, 15, v53
	v_lshl_add_u32 v27, v27, 2, v56
	ds_read_b32 v18, v27
	v_cmp_gt_u32_e64 s[60:61], 15, v31
	v_lshlrev_b32_e64 v28, v29, 1
	s_nop 0
	v_cndmask_b32_e64 v28, 0, v28, s[60:61]
	v_cndmask_b32_e64 v30, 0, v28, s[62:63]
	v_sub_u32_e32 v28, v28, v30
	v_add_u32_e32 v24, v24, v30
	v_add_u32_e32 v25, v25, v28
	v_cmp_eq_u32_e64 s[8:9], 0, v141
	v_cmp_eq_u32_e64 s[10:11], 1, v141
	v_cmp_eq_u32_e64 s[12:13], 2, v141
	v_cmp_eq_u32_e64 s[24:25], 3, v141
	v_cmp_eq_u32_e64 s[26:27], 4, v141
	v_cmp_eq_u32_e64 s[28:29], 5, v141
	v_cmp_eq_u32_e64 s[30:31], 6, v141
	v_cmp_eq_u32_e64 s[34:35], 7, v141
	v_cmp_eq_u32_e64 s[36:37], 8, v141
	v_cmp_eq_u32_e64 s[38:39], 9, v141
	v_cmp_eq_u32_e64 s[40:41], 10, v141
	v_cmp_eq_u32_e64 s[42:43], 11, v141
	v_cmp_eq_u32_e64 s[44:45], 12, v141
	v_cmp_eq_u32_e64 s[46:47], 13, v141
	v_cmp_eq_u32_e64 s[60:61], 14, v141
	v_cmp_eq_u32_e64 s[62:63], 15, v141
	s_waitcnt lgkmcnt(0)
	v_cmp_gt_u32_e64 s[4:5], 16, v53
	v_add_f32_e32 v17, v17, v18
	v_lshl_add_u32 v44, v19, 7, v21
	v_cndmask_b32_e64 v17, v26, v17, s[4:5]
	v_cndmask_b32_e64 v0, v0, v17, s[8:9]
	v_cndmask_b32_e64 v1, v1, v17, s[10:11]
	v_cndmask_b32_e64 v2, v2, v17, s[12:13]
	v_cndmask_b32_e64 v3, v3, v17, s[24:25]
	v_cndmask_b32_e64 v4, v4, v17, s[26:27]
	v_cndmask_b32_e64 v5, v5, v17, s[28:29]
	v_cndmask_b32_e64 v6, v6, v17, s[30:31]
	v_cndmask_b32_e64 v7, v7, v17, s[34:35]
	v_cndmask_b32_e64 v8, v8, v17, s[36:37]
	v_cndmask_b32_e64 v9, v9, v17, s[38:39]
	v_cndmask_b32_e64 v10, v10, v17, s[40:41]
	v_cndmask_b32_e64 v11, v11, v17, s[42:43]
	v_cndmask_b32_e64 v12, v12, v17, s[44:45]
	v_cndmask_b32_e64 v13, v13, v17, s[46:47]
	v_cndmask_b32_e64 v14, v14, v17, s[60:61]
	v_cndmask_b32_e64 v15, v15, v17, s[62:63]
	v_cmp_gt_f32_e64 s[8:9], v1, v0
	v_cmp_gt_f32_e64 s[10:11], v3, v2
	v_cmp_gt_f32_e64 s[12:13], v5, v4
	v_cmp_gt_f32_e64 s[24:25], v7, v6
	v_cmp_gt_f32_e64 s[26:27], v9, v8
	v_cmp_gt_f32_e64 s[28:29], v11, v10
	v_cmp_gt_f32_e64 s[30:31], v13, v12
	v_cmp_gt_f32_e64 s[34:35], v15, v14
	v_cndmask_b32_e64 v16, v0, v1, s[8:9]
	v_cndmask_b32_e64 v141, 0, 1, s[8:9]
	v_cndmask_b32_e64 v17, v2, v3, s[10:11]
	v_cndmask_b32_e64 v142, 2, 3, s[10:11]
	v_cndmask_b32_e64 v18, v4, v5, s[12:13]
	v_cndmask_b32_e64 v143, 4, 5, s[12:13]
	v_cndmask_b32_e64 v19, v6, v7, s[24:25]
	v_cndmask_b32_e64 v144, 6, 7, s[24:25]
	v_cndmask_b32_e64 v20, v8, v9, s[26:27]
	v_cndmask_b32_e64 v145, 8, 9, s[26:27]
	v_cndmask_b32_e64 v21, v10, v11, s[28:29]
	v_cndmask_b32_e64 v146, 10, 11, s[28:29]
	v_cndmask_b32_e64 v22, v12, v13, s[30:31]
	v_cndmask_b32_e64 v147, 12, 13, s[30:31]
	v_cndmask_b32_e64 v23, v14, v15, s[34:35]
; DI void peer_topk_item(const Params& p, int tt128, int head, char* smem) {
;     ...
; #pragma unroll
;     for (int r = 0; r < 16; ++r) {
;       float best = cur[0]; int bi = 0; int bj = pp[0];
; #pragma unroll
;       for (int i = 1; i < 16; ++i) if (cur[i] > best) { best = cur[i]; bi = i; bj = pp[i]; }
;       sel[r] = best;
;       eid[r] = (int)ai[bi] * 128 + (int)bi_[bj];
;       const int nj = bj + 1;
;       const float nv = (nj < 16) ? (av[bi] + bv[nj & 15]) : -INFINITY;
; #pragma unroll
;       for (int i = 0; i < 16; ++i) { cur[i] = (i == bi) ? nv : cur[i]; pp[i] = (i == bi) ? nj : pp[i]; }
;     }
	v_cndmask_b32_e64 v148, 14, 15, s[34:35]
	v_cmp_gt_f32_e64 s[8:9], v17, v16
	v_cmp_gt_f32_e64 s[10:11], v19, v18
	v_cmp_gt_f32_e64 s[12:13], v21, v20
	v_cmp_gt_f32_e64 s[24:25], v23, v22
	v_cndmask_b32_e64 v16, v16, v17, s[8:9]
	v_cndmask_b32_e64 v141, v141, v142, s[8:9]
	v_cndmask_b32_e64 v18, v18, v19, s[10:11]
	v_cndmask_b32_e64 v143, v143, v144, s[10:11]
	v_cndmask_b32_e64 v20, v20, v21, s[12:13]
	v_cndmask_b32_e64 v145, v145, v146, s[12:13]
	v_cndmask_b32_e64 v22, v22, v23, s[24:25]
	v_cndmask_b32_e64 v147, v147, v148, s[24:25]
	v_cmp_gt_f32_e64 s[8:9], v18, v16
	v_cmp_gt_f32_e64 s[10:11], v22, v20
	s_nop 0
	v_cndmask_b32_e64 v16, v16, v18, s[8:9]
	v_cndmask_b32_e64 v141, v141, v143, s[8:9]
	v_cndmask_b32_e64 v20, v20, v22, s[10:11]
	v_cndmask_b32_e64 v145, v145, v147, s[10:11]
	v_cmp_gt_f32_e64 s[8:9], v20, v16
	s_nop 1
	v_cndmask_b32_e64 v16, v16, v20, s[8:9]
	v_cndmask_b32_e64 v141, v141, v145, s[8:9]
	v_mov_b32_e32 v137, v16
	v_add_u32_e32 v28, v57, v141
	ds_read_u8 v19, v28
	v_cmp_gt_u32_e64 s[62:63], 8, v141
	v_and_b32_e32 v29, 7, v141
	v_lshlrev_b32_e32 v29, 2, v29
	v_cndmask_b32_e64 v30, v25, v24, s[62:63]
	v_bfe_u32 v31, v30, v29, 4
	v_add_u32_e32 v52, v58, v31
	ds_read_u8 v21, v52
	v_lshl_add_u32 v27, v141, 2, v55
	ds_read_b32 v17, v27
	v_add_u32_e32 v53, 1, v31
	v_and_b32_e32 v27, 15, v53
	v_lshl_add_u32 v27, v27, 2, v56
	ds_read_b32 v18, v27
	v_cmp_gt_u32_e64 s[60:61], 15, v31
	v_lshlrev_b32_e64 v28, v29, 1
	s_nop 0
	v_cndmask_b32_e64 v28, 0, v28, s[60:61]
	v_cndmask_b32_e64 v30, 0, v28, s[62:63]
	v_sub_u32_e32 v28, v28, v30
	v_add_u32_e32 v24, v24, v30
	v_add_u32_e32 v25, v25, v28
	v_cmp_eq_u32_e64 s[8:9], 0, v141
	v_cmp_eq_u32_e64 s[10:11], 1, v141
	v_cmp_eq_u32_e64 s[12:13], 2, v141
	v_cmp_eq_u32_e64 s[24:25], 3, v141
	v_cmp_eq_u32_e64 s[26:27], 4, v141
	v_cmp_eq_u32_e64 s[28:29], 5, v141
	v_cmp_eq_u32_e64 s[30:31], 6, v141
	v_cmp_eq_u32_e64 s[34:35], 7, v141
	v_cmp_eq_u32_e64 s[36:37], 8, v141
	v_cmp_eq_u32_e64 s[38:39], 9, v141
	v_cmp_eq_u32_e64 s[40:41], 10, v141
	v_cmp_eq_u32_e64 s[42:43], 11, v141
	v_cmp_eq_u32_e64 s[44:45], 12, v141
	v_cmp_eq_u32_e64 s[46:47], 13, v141
	v_cmp_eq_u32_e64 s[60:61], 14, v141
	v_cmp_eq_u32_e64 s[62:63], 15, v141
	s_waitcnt lgkmcnt(0)
	v_cmp_gt_u32_e64 s[4:5], 16, v53
	v_add_f32_e32 v17, v17, v18
	v_lshl_add_u32 v45, v19, 7, v21
	v_cndmask_b32_e64 v17, v26, v17, s[4:5]
	v_cndmask_b32_e64 v0, v0, v17, s[8:9]
	v_cndmask_b32_e64 v1, v1, v17, s[10:11]
	v_cndmask_b32_e64 v2, v2, v17, s[12:13]
	v_cndmask_b32_e64 v3, v3, v17, s[24:25]
	v_cndmask_b32_e64 v4, v4, v17, s[26:27]
	v_cndmask_b32_e64 v5, v5, v17, s[28:29]
	v_cndmask_b32_e64 v6, v6, v17, s[30:31]
	v_cndmask_b32_e64 v7, v7, v17, s[34:35]
	v_cndmask_b32_e64 v8, v8, v17, s[36:37]
	v_cndmask_b32_e64 v9, v9, v17, s[38:39]
	v_cndmask_b32_e64 v10, v10, v17, s[40:41]
	v_cndmask_b32_e64 v11, v11, v17, s[42:43]
	v_cndmask_b32_e64 v12, v12, v17, s[44:45]
	v_cndmask_b32_e64 v13, v13, v17, s[46:47]
	v_cndmask_b32_e64 v14, v14, v17, s[60:61]
	v_cndmask_b32_e64 v15, v15, v17, s[62:63]
	v_cmp_gt_f32_e64 s[8:9], v1, v0
	v_cmp_gt_f32_e64 s[10:11], v3, v2
	v_cmp_gt_f32_e64 s[12:13], v5, v4
	v_cmp_gt_f32_e64 s[24:25], v7, v6
	v_cmp_gt_f32_e64 s[26:27], v9, v8
	v_cmp_gt_f32_e64 s[28:29], v11, v10
	v_cmp_gt_f32_e64 s[30:31], v13, v12
	v_cmp_gt_f32_e64 s[34:35], v15, v14
	v_cndmask_b32_e64 v16, v0, v1, s[8:9]
	v_cndmask_b32_e64 v141, 0, 1, s[8:9]
	v_cndmask_b32_e64 v17, v2, v3, s[10:11]
	v_cndmask_b32_e64 v142, 2, 3, s[10:11]
	v_cndmask_b32_e64 v18, v4, v5, s[12:13]
	v_cndmask_b32_e64 v143, 4, 5, s[12:13]
	v_cndmask_b32_e64 v19, v6, v7, s[24:25]
	v_cndmask_b32_e64 v144, 6, 7, s[24:25]
	v_cndmask_b32_e64 v20, v8, v9, s[26:27]
	v_cndmask_b32_e64 v145, 8, 9, s[26:27]
	v_cndmask_b32_e64 v21, v10, v11, s[28:29]
	v_cndmask_b32_e64 v146, 10, 11, s[28:29]
	v_cndmask_b32_e64 v22, v12, v13, s[30:31]
	v_cndmask_b32_e64 v147, 12, 13, s[30:31]
	v_cndmask_b32_e64 v23, v14, v15, s[34:35]
	v_cndmask_b32_e64 v148, 14, 15, s[34:35]
	v_cmp_gt_f32_e64 s[8:9], v17, v16
	v_cmp_gt_f32_e64 s[10:11], v19, v18
	v_cmp_gt_f32_e64 s[12:13], v21, v20
	v_cmp_gt_f32_e64 s[24:25], v23, v22
	v_cndmask_b32_e64 v16, v16, v17, s[8:9]
	v_cndmask_b32_e64 v141, v141, v142, s[8:9]
	v_cndmask_b32_e64 v18, v18, v19, s[10:11]
	v_cndmask_b32_e64 v143, v143, v144, s[10:11]
	v_cndmask_b32_e64 v20, v20, v21, s[12:13]
	v_cndmask_b32_e64 v145, v145, v146, s[12:13]
	v_cndmask_b32_e64 v22, v22, v23, s[24:25]
	v_cndmask_b32_e64 v147, v147, v148, s[24:25]
	v_cmp_gt_f32_e64 s[8:9], v18, v16
	v_cmp_gt_f32_e64 s[10:11], v22, v20
	s_nop 0
	v_cndmask_b32_e64 v16, v16, v18, s[8:9]
	v_cndmask_b32_e64 v141, v141, v143, s[8:9]
	v_cndmask_b32_e64 v20, v20, v22, s[10:11]
	v_cndmask_b32_e64 v145, v145, v147, s[10:11]
	v_cmp_gt_f32_e64 s[8:9], v20, v16
	s_nop 1
	v_cndmask_b32_e64 v16, v16, v20, s[8:9]
	v_cndmask_b32_e64 v141, v141, v145, s[8:9]
	v_mov_b32_e32 v138, v16
	v_add_u32_e32 v28, v57, v141
	ds_read_u8 v19, v28
	v_cmp_gt_u32_e64 s[62:63], 8, v141
	v_and_b32_e32 v29, 7, v141
	v_lshlrev_b32_e32 v29, 2, v29
	v_cndmask_b32_e64 v30, v25, v24, s[62:63]
	v_bfe_u32 v31, v30, v29, 4
	v_add_u32_e32 v52, v58, v31
	ds_read_u8 v21, v52
	v_lshl_add_u32 v27, v141, 2, v55
	ds_read_b32 v17, v27
	v_add_u32_e32 v53, 1, v31
	v_and_b32_e32 v27, 15, v53
	v_lshl_add_u32 v27, v27, 2, v56
	ds_read_b32 v18, v27
	v_cmp_gt_u32_e64 s[60:61], 15, v31
	v_lshlrev_b32_e64 v28, v29, 1
	s_nop 0
	v_cndmask_b32_e64 v28, 0, v28, s[60:61]
	v_cndmask_b32_e64 v30, 0, v28, s[62:63]
	v_sub_u32_e32 v28, v28, v30
	v_add_u32_e32 v24, v24, v30
	v_add_u32_e32 v25, v25, v28
	v_cmp_eq_u32_e64 s[8:9], 0, v141
	v_cmp_eq_u32_e64 s[10:11], 1, v141
	v_cmp_eq_u32_e64 s[12:13], 2, v141
	v_cmp_eq_u32_e64 s[24:25], 3, v141
	v_cmp_eq_u32_e64 s[26:27], 4, v141
	v_cmp_eq_u32_e64 s[28:29], 5, v141
	v_cmp_eq_u32_e64 s[30:31], 6, v141
	v_cmp_eq_u32_e64 s[34:35], 7, v141
	v_cmp_eq_u32_e64 s[36:37], 8, v141
	v_cmp_eq_u32_e64 s[38:39], 9, v141
	v_cmp_eq_u32_e64 s[40:41], 10, v141
	v_cmp_eq_u32_e64 s[42:43], 11, v141
	v_cmp_eq_u32_e64 s[44:45], 12, v141
	v_cmp_eq_u32_e64 s[46:47], 13, v141
	v_cmp_eq_u32_e64 s[60:61], 14, v141
	v_cmp_eq_u32_e64 s[62:63], 15, v141
	s_waitcnt lgkmcnt(0)
; DI void peer_topk_item(const Params& p, int tt128, int head, char* smem) {
;     ...
;     for (int r = 0; r < 16; ++r) {
;       float best = cur[0]; int bi = 0; int bj = pp[0];
; #pragma unroll
;       for (int i = 1; i < 16; ++i) if (cur[i] > best) { best = cur[i]; bi = i; bj = pp[i]; }
;       sel[r] = best;
;       eid[r] = (int)ai[bi] * 128 + (int)bi_[bj];
;       const int nj = bj + 1;
;       const float nv = (nj < 16) ? (av[bi] + bv[nj & 15]) : -INFINITY;
; #pragma unroll
;       for (int i = 0; i < 16; ++i) { cur[i] = (i == bi) ? nv : cur[i]; pp[i] = (i == bi) ? nj : pp[i]; }
;     }
;     float sum = 0.f;
;     const float smax = sel[0];
; #pragma unroll
;     for (int r = 0; r < 16; ++r) { sel[r] = __expf(sel[r] - smax); sum += sel[r]; }
;     const float inv = 1.f / sum;
;     int* eo = (int*)(p.ws + OFF_EIDX) + (size_t)(tok0 + tid) * 128 + head * 16;
;     float* go = (float*)(p.ws + OFF_GATE) + (size_t)(tok0 + tid) * 128 + head * 16;
; #pragma unroll
;     for (int r = 0; r < 16; ++r) { eo[r] = eid[r]; go[r] = sel[r] * inv; }
	v_cmp_gt_u32_e64 s[4:5], 16, v53
	v_add_f32_e32 v17, v17, v18
	v_lshl_add_u32 v46, v19, 7, v21
	v_cndmask_b32_e64 v17, v26, v17, s[4:5]
	v_cndmask_b32_e64 v0, v0, v17, s[8:9]
	v_cndmask_b32_e64 v1, v1, v17, s[10:11]
	v_cndmask_b32_e64 v2, v2, v17, s[12:13]
	v_cndmask_b32_e64 v3, v3, v17, s[24:25]
	v_cndmask_b32_e64 v4, v4, v17, s[26:27]
	v_cndmask_b32_e64 v5, v5, v17, s[28:29]
	v_cndmask_b32_e64 v6, v6, v17, s[30:31]
	v_cndmask_b32_e64 v7, v7, v17, s[34:35]
	v_cndmask_b32_e64 v8, v8, v17, s[36:37]
	v_cndmask_b32_e64 v9, v9, v17, s[38:39]
	v_cndmask_b32_e64 v10, v10, v17, s[40:41]
	v_cndmask_b32_e64 v11, v11, v17, s[42:43]
	v_cndmask_b32_e64 v12, v12, v17, s[44:45]
	v_cndmask_b32_e64 v13, v13, v17, s[46:47]
	v_cndmask_b32_e64 v14, v14, v17, s[60:61]
	v_cndmask_b32_e64 v15, v15, v17, s[62:63]
	v_cmp_gt_f32_e64 s[8:9], v1, v0
	v_cmp_gt_f32_e64 s[10:11], v3, v2
	v_cmp_gt_f32_e64 s[12:13], v5, v4
	v_cmp_gt_f32_e64 s[24:25], v7, v6
	v_cmp_gt_f32_e64 s[26:27], v9, v8
	v_cmp_gt_f32_e64 s[28:29], v11, v10
	v_cmp_gt_f32_e64 s[30:31], v13, v12
	v_cmp_gt_f32_e64 s[34:35], v15, v14
	v_cndmask_b32_e64 v16, v0, v1, s[8:9]
	v_cndmask_b32_e64 v141, 0, 1, s[8:9]
	v_cndmask_b32_e64 v17, v2, v3, s[10:11]
	v_cndmask_b32_e64 v142, 2, 3, s[10:11]
	v_cndmask_b32_e64 v18, v4, v5, s[12:13]
	v_cndmask_b32_e64 v143, 4, 5, s[12:13]
	v_cndmask_b32_e64 v19, v6, v7, s[24:25]
	v_cndmask_b32_e64 v144, 6, 7, s[24:25]
	v_cndmask_b32_e64 v20, v8, v9, s[26:27]
	v_cndmask_b32_e64 v145, 8, 9, s[26:27]
	v_cndmask_b32_e64 v21, v10, v11, s[28:29]
	v_cndmask_b32_e64 v146, 10, 11, s[28:29]
	v_cndmask_b32_e64 v22, v12, v13, s[30:31]
	v_cndmask_b32_e64 v147, 12, 13, s[30:31]
	v_cndmask_b32_e64 v23, v14, v15, s[34:35]
	v_cndmask_b32_e64 v148, 14, 15, s[34:35]
	v_cmp_gt_f32_e64 s[8:9], v17, v16
	v_cmp_gt_f32_e64 s[10:11], v19, v18
	v_cmp_gt_f32_e64 s[12:13], v21, v20
	v_cmp_gt_f32_e64 s[24:25], v23, v22
	v_cndmask_b32_e64 v16, v16, v17, s[8:9]
	v_cndmask_b32_e64 v141, v141, v142, s[8:9]
	v_cndmask_b32_e64 v18, v18, v19, s[10:11]
	v_cndmask_b32_e64 v143, v143, v144, s[10:11]
	v_cndmask_b32_e64 v20, v20, v21, s[12:13]
	v_cndmask_b32_e64 v145, v145, v146, s[12:13]
	v_cndmask_b32_e64 v22, v22, v23, s[24:25]
	v_cndmask_b32_e64 v147, v147, v148, s[24:25]
	v_cmp_gt_f32_e64 s[8:9], v18, v16
	v_cmp_gt_f32_e64 s[10:11], v22, v20
	s_nop 0
	v_cndmask_b32_e64 v16, v16, v18, s[8:9]
	v_cndmask_b32_e64 v141, v141, v143, s[8:9]
	v_cndmask_b32_e64 v20, v20, v22, s[10:11]
	v_cndmask_b32_e64 v145, v145, v147, s[10:11]
	v_cmp_gt_f32_e64 s[8:9], v20, v16
	s_nop 1
	v_cndmask_b32_e64 v16, v16, v20, s[8:9]
	v_cndmask_b32_e64 v141, v141, v145, s[8:9]
	v_mov_b32_e32 v139, v16
	v_add_u32_e32 v28, v57, v141
	ds_read_u8 v19, v28
	v_cmp_gt_u32_e64 s[62:63], 8, v141
	v_and_b32_e32 v29, 7, v141
	v_lshlrev_b32_e32 v29, 2, v29
	v_cndmask_b32_e64 v30, v25, v24, s[62:63]
	v_bfe_u32 v31, v30, v29, 4
	v_add_u32_e32 v52, v58, v31
	ds_read_u8 v21, v52
	s_waitcnt lgkmcnt(0)
	v_lshl_add_u32 v47, v19, 7, v21
	v_sub_f32_e32 v17, v124, v124
	v_sub_f32_e32 v2, v125, v124
	v_sub_f32_e32 v3, v126, v124
	v_sub_f32_e32 v4, v127, v124
	v_sub_f32_e32 v5, v128, v124
	v_sub_f32_e32 v6, v129, v124
	v_sub_f32_e32 v7, v130, v124
	v_sub_f32_e32 v8, v131, v124
	v_sub_f32_e32 v9, v132, v124
	v_sub_f32_e32 v10, v133, v124
	v_sub_f32_e32 v11, v134, v124
	v_sub_f32_e32 v12, v135, v124
	v_sub_f32_e32 v13, v136, v124
	v_sub_f32_e32 v14, v137, v124
	v_sub_f32_e32 v15, v138, v124
	v_sub_f32_e32 v16, v139, v124
	v_mul_f32_e32 v17, 0x3fb8aa3b, v17
	v_mul_f32_e32 v2, 0x3fb8aa3b, v2
	v_mul_f32_e32 v3, 0x3fb8aa3b, v3
	v_mul_f32_e32 v4, 0x3fb8aa3b, v4
	v_mul_f32_e32 v5, 0x3fb8aa3b, v5
	v_mul_f32_e32 v6, 0x3fb8aa3b, v6
	v_mul_f32_e32 v7, 0x3fb8aa3b, v7
	v_mul_f32_e32 v8, 0x3fb8aa3b, v8
	v_mul_f32_e32 v9, 0x3fb8aa3b, v9
	v_mul_f32_e32 v10, 0x3fb8aa3b, v10
	v_mul_f32_e32 v11, 0x3fb8aa3b, v11
	v_mul_f32_e32 v12, 0x3fb8aa3b, v12
	v_mul_f32_e32 v13, 0x3fb8aa3b, v13
	v_mul_f32_e32 v14, 0x3fb8aa3b, v14
	v_mul_f32_e32 v15, 0x3fb8aa3b, v15
	v_mul_f32_e32 v16, 0x3fb8aa3b, v16
	v_exp_f32_e32 v125, v2
	v_exp_f32_e32 v126, v3
	v_exp_f32_e32 v127, v4
	v_exp_f32_e32 v128, v5
	v_exp_f32_e32 v129, v6
	v_exp_f32_e32 v130, v7
	v_exp_f32_e32 v131, v8
	v_exp_f32_e32 v132, v9
	v_exp_f32_e32 v133, v10
	v_exp_f32_e32 v134, v11
	v_exp_f32_e32 v135, v12
	v_exp_f32_e32 v136, v13
	v_exp_f32_e32 v137, v14
	v_exp_f32_e32 v138, v15
	v_exp_f32_e32 v139, v16
	v_exp_f32_e32 v18, v17
	s_nop 0
	v_mov_b32_e32 v124, v18
	v_add_f32_e32 v0, 0, v18
	v_add_f32_e32 v0, v0, v125
	v_add_f32_e32 v0, v0, v126
	v_add_f32_e32 v0, v0, v127
	v_add_f32_e32 v0, v0, v128
	v_add_f32_e32 v0, v0, v129
	v_add_f32_e32 v0, v0, v130
	v_add_f32_e32 v0, v0, v131
	v_add_f32_e32 v0, v0, v132
	v_add_f32_e32 v0, v0, v133
	v_add_f32_e32 v0, v0, v134
	v_add_f32_e32 v0, v0, v135
	v_add_f32_e32 v0, v0, v136
	v_add_f32_e32 v0, v0, v137
	v_add_f32_e32 v0, v0, v138
	v_add_f32_e32 v0, v0, v139
	v_div_scale_f32 v17, s[8:9], v0, v0, 1.0
	v_rcp_f32_e32 v18, v17
	s_and_b32 s4, s2, 7
	s_lshl_b32 s50, s4, 6
	v_fma_f32 v19, -v17, v18, 1.0
	v_fmac_f32_e32 v18, v19, v18
	v_div_scale_f32 v19, vcc, 1.0, v0, 1.0
	v_mul_f32_e32 v20, v19, v18
	v_fma_f32 v21, -v17, v20, v19
	v_fmac_f32_e32 v20, v21, v18
	v_fma_f32 v17, -v17, v20, v19
	v_div_fmas_f32 v17, v17, v18, v20
	v_div_fixup_f32 v22, v17, v0, 1.0
	v_lshl_or_b32 v16, s33, 7, v166
	v_ashrrev_i32_e32 v17, 31, v16
	v_lshlrev_b64 v[16:17], 9, v[16:17]
	v_lshl_add_u64 v[18:19], s[96:97], 0, v[16:17]
	v_lshl_add_u64 v[18:19], v[18:19], 0, s[50:51]
	v_lshl_add_u64 v[16:17], s[48:49], 0, v[16:17]
	v_lshl_add_u64 v[16:17], v[16:17], 0, s[50:51]
	v_mul_f32_e32 v124, v124, v22
	v_mul_f32_e32 v125, v125, v22
	v_mul_f32_e32 v126, v126, v22
	v_mul_f32_e32 v127, v127, v22
	v_mul_f32_e32 v128, v128, v22
	v_mul_f32_e32 v129, v129, v22
	v_mul_f32_e32 v130, v130, v22
	v_mul_f32_e32 v131, v131, v22
	v_mul_f32_e32 v132, v132, v22
	v_mul_f32_e32 v133, v133, v22
	v_mul_f32_e32 v134, v134, v22
	v_mul_f32_e32 v135, v135, v22
	v_mul_f32_e32 v136, v136, v22
	v_mul_f32_e32 v137, v137, v22
	v_mul_f32_e32 v138, v138, v22
	v_mul_f32_e32 v139, v139, v22
	global_store_dwordx4 v[18:19], v[32:35], off
	global_store_dwordx4 v[18:19], v[36:39], off offset:16
	global_store_dwordx4 v[18:19], v[40:43], off offset:32
	global_store_dwordx4 v[18:19], v[44:47], off offset:48
	global_store_dwordx4 v[16:17], v[124:127], off
	global_store_dwordx4 v[16:17], v[128:131], off offset:16
	global_store_dwordx4 v[16:17], v[132:135], off offset:32
	global_store_dwordx4 v[16:17], v[136:139], off offset:48
	s_branch .LBB0_962
